# v124 + three s_nop per K-loop iteration replaced by pointer-add pairs moved from the loop head/tail + 32-bit scalar tile index in the FFN-up/W_in headers (all removal-only edits combined)
# speedup vs baseline: 1.0107x; 1.0107x over previous
; #define PG8_STAGE(bufoff, gbase, voff) do { _Pragma("unroll") for (int _i = 0; _i < 2; ++_i) \
;         __builtin_amdgcn_global_load_lds((const unsigned*)((const char*)(gbase) + (voff)[_i]), (PG8_LAS unsigned*)(lds + (bufoff) + ldsw + _i * 8192), 16, 0, 0); } while (0)
; #define PG8_LDA(dst, b, h) do { _Pragma("unroll") for (int m = 0; m < 4; ++m) _Pragma("unroll") for (int k = 0; k < 2; ++k) dst[m][k] = *(const PG8_LAS bf16x8*)(lds + PG8_SA(b, h) + aoff + m * 2048 + k * 1024); } while (0)
; #define PG8_LDB(dst, b, h) do { _Pragma("unroll") for (int n = 0; n < 2; ++n) _Pragma("unroll") for (int k = 0; k < 2; ++k) dst[n][k] = *(const PG8_LAS bf16x8*)(lds + PG8_SB(b, h) + boff + n * 2048 + k * 1024); } while (0)
; #define PG8_MMA(ai, bj, At, Bt) do { __builtin_amdgcn_s_setprio(1); _Pragma("unroll") for (int m = 0; m < 4; ++m) _Pragma("unroll") for (int n = 0; n < 2; ++n) _Pragma("unroll") for (int k = 0; k < 2; ++k) \
;         acc[ai][bj][m][n] = __builtin_amdgcn_mfma_f32_16x16x32_bf16(Bt[n][k], At[m][k], acc[ai][bj][m][n], 0, 0, 0); __builtin_amdgcn_s_setprio(0); } while (0)
; #define PG8_BAR __builtin_amdgcn_s_barrier()
; template <class Epi, class Sched, bool ALIGN_EPI = false, bool SP2 = false>
; __device__ __forceinline__ void gemm_phase(PG8_LAS unsigned char* lds, const Gemm g, const Sched& S, const Epi& E) {
;     ...
;         const bool has_next = S.next(ui + 1, nxt);
;         const char* nA = has_next ? (const char*)g.A + (size_t)nxt.pm * tstep : cA; const char* nB = has_next ? (const char*)g.Bt + (size_t)nxt.pn * tstep : cB;
;         for (int t = 0; t < nt; t += 2) {
;             const bool last = (t == nt - 2);
;             const char* a1 = cA + (size_t)(t + 1) * kstep;
;             const char* a2 = last ? nA : cA + (size_t)(t + 2) * kstep; const char* b2 = last ? nB : cB + (size_t)(t + 2) * kstep;
;             const char* a3 = a2 + kstep; const char* b3 = b2 + kstep;
;             if (last && has_next) S.a_ready(nxt);
;             if constexpr (SP2) {
;             PG8_LDB(B0, 0, 0); PG8_LDB(B1, 0, 1); PG8_SCHED; PG8_LDA(At, 0, 0); PG8_STAGE(PG8_SA(1, 1), a1 + hstep, voffA);
;             PG8_WAIT_V(8); PG8_WAIT_L(0); PG8_BAR; PG8_MMA(0, 0, At, B0); PG8_MMA(0, 1, At, B1); PG8_BAR; PG8_SCHED;
;             PG8_LDA(At, 0, 1); PG8_STAGE(PG8_SB(0, 0), b2, voffB); PG8_STAGE(PG8_SB(0, 1), b2 + hstep, voffB); PG8_STAGE(PG8_SA(0, 0), a2, voffA);
.LBB0_1129:
	s_ashr_i32 s79, s78, 31
	s_lshl_b64 s[22:23], s[78:79], 19
	v_readlane_b32 s5, v255, 15
	s_add_u32 s80, s5, s22
	s_addc_u32 s81, s61, s23
	s_and_b64 s[22:23], s[2:3], exec
	s_cselect_b32 s5, s81, s7
	s_cselect_b32 s9, s80, s6
	s_ashr_i32 s77, s76, 31
	s_lshl_b64 s[22:23], s[76:77], 19
	s_add_u32 s82, s55, s22
	s_addc_u32 s83, s56, s23
	s_and_b64 s[22:23], s[2:3], exec
	s_cselect_b32 s22, s83, s11
	s_cselect_b32 s23, s82, s10
	s_add_u32 s6, s6, 0xc000
	s_addc_u32 s7, s7, 0
	s_add_u32 s30, s10, 0x10000
	v_mov_b32_e32 v0, 0
	s_addc_u32 s37, s11, 0
	s_mov_b32 s40, -2
	v_add_u32_e32 v246, 0x10000, v192
	s_add_u32 s10, s6, 0x4000
	s_addc_u32 s11, s7, 0
	s_cmp_eq_u32 s40, 12
	s_cselect_b32 s86, s9, s10
	s_cselect_b32 s87, s5, s11
	s_cselect_b32 s84, s23, s30
	s_cselect_b32 s85, s22, s37
	ds_read_b128 v[16:19], v246
	ds_read_b128 v[20:23], v246 offset:1024
	ds_read_b128 v[24:27], v246 offset:2048
	ds_read_b128 v[32:35], v246 offset:3072
	ds_read_b128 v[48:51], v246 offset:16384
	ds_read_b128 v[52:55], v246 offset:17408
	ds_read_b128 v[56:59], v246 offset:18432
	ds_read_b128 v[60:63], v246 offset:19456
	s_add_i32 m0, s33, 0xc000
	ds_read_b128 v[160:163], v193
	ds_read_b128 v[164:167], v193 offset:1024
	ds_read_b128 v[180:183], v193 offset:2048
	ds_read_b128 v[184:187], v193 offset:3072
	ds_read_b128 v[188:191], v193 offset:4096
	ds_read_b128 v[194:197], v193 offset:5120
	ds_read_b128 v[198:201], v193 offset:6144
	ds_read_b128 v[202:205], v193 offset:7168
	global_load_lds_dwordx4 v176, s[6:7]
	s_add_i32 m0, s33, 0xe000
	s_add_u32 s10, s86, 0x8000
	s_addc_u32 s11, s87, 0
	global_load_lds_dwordx4 v178, s[6:7]
	s_waitcnt vmcnt(8) lgkmcnt(0)
	s_barrier
	v_mfma_f32_16x16x32_bf16 v[156:159], v[16:19], v[160:163], 0
	v_mfma_f32_16x16x32_bf16 v[152:155], v[24:27], v[160:163], 0
	v_mfma_f32_16x16x32_bf16 v[140:143], v[16:19], v[180:183], 0
	v_mfma_f32_16x16x32_bf16 v[136:139], v[24:27], v[180:183], 0
	v_mfma_f32_16x16x32_bf16 v[124:127], v[16:19], v[188:191], 0
	v_mfma_f32_16x16x32_bf16 v[120:123], v[24:27], v[188:191], 0
	v_mfma_f32_16x16x32_bf16 v[108:111], v[16:19], v[198:201], 0
	v_mfma_f32_16x16x32_bf16 v[104:107], v[24:27], v[198:201], 0
	v_mfma_f32_16x16x32_bf16 v[156:159], v[20:23], v[164:167], v[156:159]
	v_mfma_f32_16x16x32_bf16 v[152:155], v[32:35], v[164:167], v[152:155]
	v_mfma_f32_16x16x32_bf16 v[140:143], v[20:23], v[184:187], v[140:143]
	v_mfma_f32_16x16x32_bf16 v[136:139], v[32:35], v[184:187], v[136:139]
	v_mfma_f32_16x16x32_bf16 v[124:127], v[20:23], v[194:197], v[124:127]
	v_mfma_f32_16x16x32_bf16 v[120:123], v[32:35], v[194:197], v[120:123]
	v_mfma_f32_16x16x32_bf16 v[108:111], v[20:23], v[202:205], v[108:111]
	v_mfma_f32_16x16x32_bf16 v[104:107], v[32:35], v[202:205], v[104:107]
	v_mfma_f32_16x16x32_bf16 v[148:151], v[48:51], v[160:163], 0
	v_mfma_f32_16x16x32_bf16 v[144:147], v[56:59], v[160:163], 0
	v_mfma_f32_16x16x32_bf16 v[132:135], v[48:51], v[180:183], 0
	v_mfma_f32_16x16x32_bf16 v[128:131], v[56:59], v[180:183], 0
	v_mfma_f32_16x16x32_bf16 v[116:119], v[48:51], v[188:191], 0
	v_mfma_f32_16x16x32_bf16 v[112:115], v[56:59], v[188:191], 0
	v_mfma_f32_16x16x32_bf16 v[100:103], v[48:51], v[198:201], 0
	v_mfma_f32_16x16x32_bf16 v[96:99], v[56:59], v[198:201], 0
	v_mfma_f32_16x16x32_bf16 v[148:151], v[52:55], v[164:167], v[148:151]
	v_mfma_f32_16x16x32_bf16 v[144:147], v[60:63], v[164:167], v[144:147]
	v_mfma_f32_16x16x32_bf16 v[132:135], v[52:55], v[184:187], v[132:135]
	v_mfma_f32_16x16x32_bf16 v[128:131], v[60:63], v[184:187], v[128:131]
	v_mfma_f32_16x16x32_bf16 v[116:119], v[52:55], v[194:197], v[116:119]
	v_mfma_f32_16x16x32_bf16 v[112:115], v[60:63], v[194:197], v[112:115]
	v_mfma_f32_16x16x32_bf16 v[100:103], v[52:55], v[202:205], v[100:103]
	v_mfma_f32_16x16x32_bf16 v[96:99], v[60:63], v[202:205], v[96:99]
	s_barrier
	s_add_i32 m0, s57, 0x10000
	ds_read_b128 v[160:163], v193 offset:16384
	ds_read_b128 v[164:167], v193 offset:17408
	ds_read_b128 v[180:183], v193 offset:18432
	ds_read_b128 v[184:187], v193 offset:19456
	ds_read_b128 v[188:191], v193 offset:20480
	ds_read_b128 v[194:197], v193 offset:21504
	ds_read_b128 v[198:201], v193 offset:22528
	ds_read_b128 v[202:205], v193 offset:23552
	global_load_lds_dwordx4 v170, s[84:85]
	s_add_i32 m0, s57, 0x12000
	s_add_u32 s88, s84, 0x4000
	s_addc_u32 s89, s85, 0
	global_load_lds_dwordx4 v174, s[84:85]
	s_add_i32 m0, s57, 0x14000
	s_add_u32 s6, s6, 0x10000
	s_addc_u32 s7, s7, 0
	global_load_lds_dwordx4 v170, s[88:89]
	s_add_i32 m0, s57, 0x16000
	s_add_u32 s30, s30, 0x10000
	s_addc_u32 s37, s37, 0
	global_load_lds_dwordx4 v174, s[88:89]
	s_mov_b32 m0, s33
	s_nop 0
	global_load_lds_dwordx4 v168, s[86:87]
	s_mov_b32 m0, s42
	s_nop 0
	global_load_lds_dwordx4 v172, s[86:87]
	s_waitcnt vmcnt(8) lgkmcnt(0)
	s_barrier
; #define PG8_STAGE(bufoff, gbase, voff) do { _Pragma("unroll") for (int _i = 0; _i < 2; ++_i) \
;         __builtin_amdgcn_global_load_lds((const unsigned*)((const char*)(gbase) + (voff)[_i]), (PG8_LAS unsigned*)(lds + (bufoff) + ldsw + _i * 8192), 16, 0, 0); } while (0)
; #define PG8_LDA(dst, b, h) do { _Pragma("unroll") for (int m = 0; m < 4; ++m) _Pragma("unroll") for (int k = 0; k < 2; ++k) dst[m][k] = *(const PG8_LAS bf16x8*)(lds + PG8_SA(b, h) + aoff + m * 2048 + k * 1024); } while (0)
; #define PG8_LDB(dst, b, h) do { _Pragma("unroll") for (int n = 0; n < 2; ++n) _Pragma("unroll") for (int k = 0; k < 2; ++k) dst[n][k] = *(const PG8_LAS bf16x8*)(lds + PG8_SB(b, h) + boff + n * 2048 + k * 1024); } while (0)
; #define PG8_MMA(ai, bj, At, Bt) do { __builtin_amdgcn_s_setprio(1); _Pragma("unroll") for (int m = 0; m < 4; ++m) _Pragma("unroll") for (int n = 0; n < 2; ++n) _Pragma("unroll") for (int k = 0; k < 2; ++k) \
;         acc[ai][bj][m][n] = __builtin_amdgcn_mfma_f32_16x16x32_bf16(Bt[n][k], At[m][k], acc[ai][bj][m][n], 0, 0, 0); __builtin_amdgcn_s_setprio(0); } while (0)
; #define PG8_WAIT_V(n) asm volatile("s_waitcnt vmcnt(" #n ")" ::: "memory")
; #define PG8_WAIT_L(n) asm volatile("s_waitcnt lgkmcnt(" #n ")" ::: "memory")
; #define PG8_BAR __builtin_amdgcn_s_barrier()
; #define PG8_SCHED __builtin_amdgcn_sched_barrier(0)
; template <class Epi, class Sched, bool ALIGN_EPI = false, bool SP2 = false>
; __device__ __forceinline__ void gemm_phase(PG8_LAS unsigned char* lds, const Gemm g, const Sched& S, const Epi& E) {
;     ...
;             PG8_WAIT_V(8); PG8_WAIT_L(0); PG8_BAR; PG8_MMA(0, 0, At, B0); PG8_MMA(0, 1, At, B1); PG8_BAR; PG8_SCHED;
;             PG8_LDA(At, 0, 1); PG8_STAGE(PG8_SB(0, 0), b2, voffB); PG8_STAGE(PG8_SB(0, 1), b2 + hstep, voffB); PG8_STAGE(PG8_SA(0, 0), a2, voffA);
;             PG8_WAIT_V(8); PG8_WAIT_L(0); PG8_BAR; PG8_MMA(1, 0, At, B0); PG8_MMA(1, 1, At, B1); PG8_BAR; PG8_SCHED;
;             PG8_LDB(B0, 1, 0); PG8_LDB(B1, 1, 1); PG8_SCHED; PG8_LDA(At, 1, 0); PG8_STAGE(PG8_SA(0, 1), a2 + hstep, voffA);
;             PG8_WAIT_V(8); PG8_WAIT_L(0); PG8_BAR; PG8_MMA(0, 0, At, B0); PG8_MMA(0, 1, At, B1); PG8_BAR; PG8_SCHED;
	v_mfma_f32_16x16x32_bf16 v[92:95], v[16:19], v[160:163], 0
	v_mfma_f32_16x16x32_bf16 v[88:91], v[24:27], v[160:163], 0
	v_mfma_f32_16x16x32_bf16 v[76:79], v[16:19], v[180:183], 0
	v_mfma_f32_16x16x32_bf16 v[72:75], v[24:27], v[180:183], 0
	v_mfma_f32_16x16x32_bf16 v[44:47], v[16:19], v[188:191], 0
	v_mfma_f32_16x16x32_bf16 v[40:43], v[24:27], v[188:191], 0
	v_mfma_f32_16x16x32_bf16 v[12:15], v[16:19], v[198:201], 0
	v_mfma_f32_16x16x32_bf16 v[8:11], v[24:27], v[198:201], 0
	v_mfma_f32_16x16x32_bf16 v[92:95], v[20:23], v[164:167], v[92:95]
	v_mfma_f32_16x16x32_bf16 v[88:91], v[32:35], v[164:167], v[88:91]
	v_mfma_f32_16x16x32_bf16 v[76:79], v[20:23], v[184:187], v[76:79]
	v_mfma_f32_16x16x32_bf16 v[72:75], v[32:35], v[184:187], v[72:75]
	v_mfma_f32_16x16x32_bf16 v[44:47], v[20:23], v[194:197], v[44:47]
	v_mfma_f32_16x16x32_bf16 v[40:43], v[32:35], v[194:197], v[40:43]
	v_mfma_f32_16x16x32_bf16 v[12:15], v[20:23], v[202:205], v[12:15]
	v_mfma_f32_16x16x32_bf16 v[8:11], v[32:35], v[202:205], v[8:11]
	v_mfma_f32_16x16x32_bf16 v[36:39], v[48:51], v[188:191], 0
	v_mfma_f32_16x16x32_bf16 v[28:31], v[56:59], v[188:191], 0
	v_mfma_f32_16x16x32_bf16 v[4:7], v[48:51], v[198:201], 0
	v_mfma_f32_16x16x32_bf16 v[0:3], v[56:59], v[198:201], 0
	v_mfma_f32_16x16x32_bf16 v[16:19], v[48:51], v[160:163], 0
	v_mfma_f32_16x16x32_bf16 v[20:23], v[56:59], v[160:163], 0
	v_mfma_f32_16x16x32_bf16 v[24:27], v[48:51], v[180:183], 0
	v_mfma_f32_16x16x32_bf16 v[32:35], v[56:59], v[180:183], 0
	v_mfma_f32_16x16x32_bf16 v[36:39], v[52:55], v[194:197], v[36:39]
	v_mfma_f32_16x16x32_bf16 v[28:31], v[60:63], v[194:197], v[28:31]
	v_mfma_f32_16x16x32_bf16 v[4:7], v[52:55], v[202:205], v[4:7]
	v_mfma_f32_16x16x32_bf16 v[0:3], v[60:63], v[202:205], v[0:3]
	v_mfma_f32_16x16x32_bf16 v[16:19], v[52:55], v[164:167], v[16:19]
	v_mfma_f32_16x16x32_bf16 v[20:23], v[60:63], v[164:167], v[20:23]
	v_mfma_f32_16x16x32_bf16 v[24:27], v[52:55], v[184:187], v[24:27]
	v_mfma_f32_16x16x32_bf16 v[32:35], v[60:63], v[184:187], v[32:35]
	s_barrier
	ds_read_b128 v[48:51], v246 offset:32768
	ds_read_b128 v[52:55], v246 offset:33792
	ds_read_b128 v[56:59], v246 offset:34816
	ds_read_b128 v[60:63], v246 offset:35840
	ds_read_b128 v[160:163], v246 offset:49152
	ds_read_b128 v[164:167], v246 offset:50176
	ds_read_b128 v[180:183], v246 offset:51200
	ds_read_b128 v[184:187], v246 offset:52224
	s_add_u32 s86, s86, 0x4000
	s_addc_u32 s87, s87, 0
	s_mov_b32 m0, s64
	ds_read_b128 v[64:67], v193 offset:32768
	ds_read_b128 v[68:71], v193 offset:33792
	ds_read_b128 v[80:83], v193 offset:34816
	ds_read_b128 v[84:87], v193 offset:35840
	ds_read_b128 v[188:191], v193 offset:36864
	ds_read_b128 v[194:197], v193 offset:37888
	ds_read_b128 v[198:201], v193 offset:38912
	ds_read_b128 v[202:205], v193 offset:39936
	global_load_lds_dwordx4 v168, s[86:87]
	s_mov_b32 m0, s65
	s_nop 0
	global_load_lds_dwordx4 v172, s[86:87]
	s_waitcnt vmcnt(8) lgkmcnt(0)
	s_barrier
	v_mfma_f32_16x16x32_bf16 v[156:159], v[48:51], v[64:67], v[156:159]
	v_mfma_f32_16x16x32_bf16 v[152:155], v[56:59], v[64:67], v[152:155]
	v_mfma_f32_16x16x32_bf16 v[140:143], v[48:51], v[80:83], v[140:143]
	v_mfma_f32_16x16x32_bf16 v[136:139], v[56:59], v[80:83], v[136:139]
	v_mfma_f32_16x16x32_bf16 v[124:127], v[48:51], v[188:191], v[124:127]
	v_mfma_f32_16x16x32_bf16 v[120:123], v[56:59], v[188:191], v[120:123]
	v_mfma_f32_16x16x32_bf16 v[108:111], v[48:51], v[198:201], v[108:111]
	v_mfma_f32_16x16x32_bf16 v[104:107], v[56:59], v[198:201], v[104:107]
	v_mfma_f32_16x16x32_bf16 v[156:159], v[52:55], v[68:71], v[156:159]
	v_mfma_f32_16x16x32_bf16 v[152:155], v[60:63], v[68:71], v[152:155]
	v_mfma_f32_16x16x32_bf16 v[140:143], v[52:55], v[84:87], v[140:143]
	v_mfma_f32_16x16x32_bf16 v[136:139], v[60:63], v[84:87], v[136:139]
	v_mfma_f32_16x16x32_bf16 v[124:127], v[52:55], v[194:197], v[124:127]
	v_mfma_f32_16x16x32_bf16 v[120:123], v[60:63], v[194:197], v[120:123]
	v_mfma_f32_16x16x32_bf16 v[108:111], v[52:55], v[202:205], v[108:111]
	v_mfma_f32_16x16x32_bf16 v[104:107], v[60:63], v[202:205], v[104:107]
	v_mfma_f32_16x16x32_bf16 v[148:151], v[160:163], v[64:67], v[148:151]
	v_mfma_f32_16x16x32_bf16 v[64:67], v[180:183], v[64:67], v[144:147]
	v_mfma_f32_16x16x32_bf16 v[144:147], v[184:187], v[68:71], v[64:67]
	v_mfma_f32_16x16x32_bf16 v[64:67], v[160:163], v[80:83], v[132:135]
	v_mfma_f32_16x16x32_bf16 v[132:135], v[164:167], v[84:87], v[64:67]
	v_mfma_f32_16x16x32_bf16 v[64:67], v[180:183], v[80:83], v[128:131]
	v_mfma_f32_16x16x32_bf16 v[128:131], v[184:187], v[84:87], v[64:67]
	v_mfma_f32_16x16x32_bf16 v[64:67], v[160:163], v[188:191], v[116:119]
	v_mfma_f32_16x16x32_bf16 v[116:119], v[164:167], v[194:197], v[64:67]
	v_mfma_f32_16x16x32_bf16 v[64:67], v[180:183], v[188:191], v[112:115]
	v_mfma_f32_16x16x32_bf16 v[112:115], v[184:187], v[194:197], v[64:67]
	v_mfma_f32_16x16x32_bf16 v[64:67], v[160:163], v[198:201], v[100:103]
	v_mfma_f32_16x16x32_bf16 v[100:103], v[164:167], v[202:205], v[64:67]
	v_mfma_f32_16x16x32_bf16 v[64:67], v[180:183], v[198:201], v[96:99]
	v_mfma_f32_16x16x32_bf16 v[148:151], v[164:167], v[68:71], v[148:151]
	v_mfma_f32_16x16x32_bf16 v[96:99], v[184:187], v[202:205], v[64:67]
	s_barrier
; #define PG8_STAGE(bufoff, gbase, voff) do { _Pragma("unroll") for (int _i = 0; _i < 2; ++_i) \
;         __builtin_amdgcn_global_load_lds((const unsigned*)((const char*)(gbase) + (voff)[_i]), (PG8_LAS unsigned*)(lds + (bufoff) + ldsw + _i * 8192), 16, 0, 0); } while (0)
; #define PG8_LDA(dst, b, h) do { _Pragma("unroll") for (int m = 0; m < 4; ++m) _Pragma("unroll") for (int k = 0; k < 2; ++k) dst[m][k] = *(const PG8_LAS bf16x8*)(lds + PG8_SA(b, h) + aoff + m * 2048 + k * 1024); } while (0)
; #define PG8_LDB(dst, b, h) do { _Pragma("unroll") for (int n = 0; n < 2; ++n) _Pragma("unroll") for (int k = 0; k < 2; ++k) dst[n][k] = *(const PG8_LAS bf16x8*)(lds + PG8_SB(b, h) + boff + n * 2048 + k * 1024); } while (0)
; template <class Epi, class Sched, bool ALIGN_EPI = false, bool SP2 = false>
; __device__ __forceinline__ void gemm_phase(PG8_LAS unsigned char* lds, const Gemm g, const Sched& S, const Epi& E) {
;     ...
;         for (int t = 0; t < nt; t += 2) {
;             const bool last = (t == nt - 2);
;             const char* a1 = cA + (size_t)(t + 1) * kstep;
;             const char* a2 = last ? nA : cA + (size_t)(t + 2) * kstep; const char* b2 = last ? nB : cB + (size_t)(t + 2) * kstep;
;             const char* a3 = a2 + kstep; const char* b3 = b2 + kstep;
;             if (last && has_next) S.a_ready(nxt);
;             if constexpr (SP2) {
;             PG8_LDB(B0, 0, 0); PG8_LDB(B1, 0, 1); PG8_SCHED; PG8_LDA(At, 0, 0); PG8_STAGE(PG8_SA(1, 1), a1 + hstep, voffA);
;             PG8_WAIT_V(8); PG8_WAIT_L(0); PG8_BAR; PG8_MMA(0, 0, At, B0); PG8_MMA(0, 1, At, B1); PG8_BAR; PG8_SCHED;
;             PG8_LDA(At, 0, 1); PG8_STAGE(PG8_SB(0, 0), b2, voffB); PG8_STAGE(PG8_SB(0, 1), b2 + hstep, voffB); PG8_STAGE(PG8_SA(0, 0), a2, voffA);
;             PG8_WAIT_V(8); PG8_WAIT_L(0); PG8_BAR; PG8_MMA(1, 0, At, B0); PG8_MMA(1, 1, At, B1); PG8_BAR; PG8_SCHED;
;             PG8_LDB(B0, 1, 0); PG8_LDB(B1, 1, 1); PG8_SCHED; PG8_LDA(At, 1, 0); PG8_STAGE(PG8_SA(0, 1), a2 + hstep, voffA);
;             PG8_WAIT_V(8); PG8_WAIT_L(0); PG8_BAR; PG8_MMA(0, 0, At, B0); PG8_MMA(0, 1, At, B1); PG8_BAR; PG8_SCHED;
;             PG8_LDA(At, 1, 1); PG8_STAGE(PG8_SB(1, 0), b3, voffB); PG8_STAGE(PG8_SB(1, 1), b3 + hstep, voffB); PG8_STAGE(PG8_SA(1, 0), a3, voffA);
;             PG8_WAIT_V(8); PG8_WAIT_L(0); PG8_BAR; PG8_MMA(1, 0, At, B0); PG8_MMA(1, 1, At, B1); PG8_BAR; PG8_SCHED;
	s_add_u32 s86, s84, 0x8000
	s_addc_u32 s87, s85, 0
	s_add_i32 m0, s57, 0x18000
	ds_read_b128 v[64:67], v193 offset:49152
	ds_read_b128 v[68:71], v193 offset:50176
	ds_read_b128 v[188:191], v193 offset:51200
	ds_read_b128 v[194:197], v193 offset:52224
	ds_read_b128 v[198:201], v193 offset:53248
	ds_read_b128 v[202:205], v193 offset:54272
	ds_read_b128 v[206:209], v193 offset:55296
	ds_read_b128 v[210:213], v193 offset:56320
	global_load_lds_dwordx4 v170, s[86:87]
	s_add_i32 m0, s57, 0x1a000
	s_add_u32 s84, s84, 0xc000
	s_addc_u32 s85, s85, 0
	global_load_lds_dwordx4 v174, s[86:87]
	s_add_i32 m0, s57, 0x1c000
	s_nop 0
	global_load_lds_dwordx4 v170, s[84:85]
	s_add_i32 m0, s57, 0x1e000
	s_nop 0
	global_load_lds_dwordx4 v174, s[84:85]
	s_mov_b32 m0, s53
	s_nop 0
	global_load_lds_dwordx4 v168, s[10:11]
	s_mov_b32 m0, s27
	s_nop 0
	global_load_lds_dwordx4 v172, s[10:11]
	s_waitcnt vmcnt(8) lgkmcnt(0)
	s_barrier
	v_mfma_f32_16x16x32_bf16 v[80:83], v[48:51], v[64:67], v[92:95]
	v_mfma_f32_16x16x32_bf16 v[92:95], v[52:55], v[68:71], v[80:83]
	v_mfma_f32_16x16x32_bf16 v[80:83], v[56:59], v[64:67], v[88:91]
	v_mfma_f32_16x16x32_bf16 v[76:79], v[48:51], v[188:191], v[76:79]
	v_mfma_f32_16x16x32_bf16 v[72:75], v[56:59], v[188:191], v[72:75]
	v_mfma_f32_16x16x32_bf16 v[44:47], v[48:51], v[198:201], v[44:47]
	v_mfma_f32_16x16x32_bf16 v[40:43], v[56:59], v[198:201], v[40:43]
	v_mfma_f32_16x16x32_bf16 v[12:15], v[48:51], v[206:209], v[12:15]
	v_mfma_f32_16x16x32_bf16 v[8:11], v[56:59], v[206:209], v[8:11]
	v_mfma_f32_16x16x32_bf16 v[88:91], v[60:63], v[68:71], v[80:83]
	v_mfma_f32_16x16x32_bf16 v[76:79], v[52:55], v[194:197], v[76:79]
	v_mfma_f32_16x16x32_bf16 v[72:75], v[60:63], v[194:197], v[72:75]
	v_mfma_f32_16x16x32_bf16 v[44:47], v[52:55], v[202:205], v[44:47]
	v_mfma_f32_16x16x32_bf16 v[40:43], v[60:63], v[202:205], v[40:43]
	v_mfma_f32_16x16x32_bf16 v[12:15], v[52:55], v[210:213], v[12:15]
	v_mfma_f32_16x16x32_bf16 v[8:11], v[60:63], v[210:213], v[8:11]
	v_mfma_f32_16x16x32_bf16 v[16:19], v[160:163], v[64:67], v[16:19]
	v_mfma_f32_16x16x32_bf16 v[84:87], v[164:167], v[68:71], v[16:19]
	v_mfma_f32_16x16x32_bf16 v[16:19], v[180:183], v[64:67], v[20:23]
	v_mfma_f32_16x16x32_bf16 v[80:83], v[184:187], v[68:71], v[16:19]
	v_mfma_f32_16x16x32_bf16 v[16:19], v[160:163], v[188:191], v[24:27]
	v_mfma_f32_16x16x32_bf16 v[68:71], v[164:167], v[194:197], v[16:19]
	v_mfma_f32_16x16x32_bf16 v[16:19], v[180:183], v[188:191], v[32:35]
	v_mfma_f32_16x16x32_bf16 v[64:67], v[184:187], v[194:197], v[16:19]
	v_mfma_f32_16x16x32_bf16 v[16:19], v[160:163], v[198:201], v[36:39]
	v_mfma_f32_16x16x32_bf16 v[36:39], v[164:167], v[202:205], v[16:19]
	v_mfma_f32_16x16x32_bf16 v[16:19], v[180:183], v[198:201], v[28:31]
	v_mfma_f32_16x16x32_bf16 v[4:7], v[160:163], v[206:209], v[4:7]
	v_mfma_f32_16x16x32_bf16 v[0:3], v[180:183], v[206:209], v[0:3]
	v_mfma_f32_16x16x32_bf16 v[28:31], v[184:187], v[202:205], v[16:19]
	v_mfma_f32_16x16x32_bf16 v[4:7], v[164:167], v[210:213], v[4:7]
	v_mfma_f32_16x16x32_bf16 v[0:3], v[184:187], v[210:213], v[0:3]
	s_barrier
	s_add_i32 s40, s40, 2
	s_cmp_gt_u32 s40, 13
.LBB0_1130:
	s_add_u32 s10, s6, 0x4000
	s_addc_u32 s11, s7, 0
	s_cmp_eq_u32 s40, 12
	s_cselect_b32 s86, s9, s10
	s_cselect_b32 s87, s5, s11
	s_cselect_b32 s84, s23, s30
	s_cselect_b32 s85, s22, s37
	ds_read_b128 v[16:19], v246
	ds_read_b128 v[20:23], v246 offset:1024
	ds_read_b128 v[24:27], v246 offset:2048
	ds_read_b128 v[32:35], v246 offset:3072
	ds_read_b128 v[48:51], v246 offset:16384
	ds_read_b128 v[52:55], v246 offset:17408
	ds_read_b128 v[56:59], v246 offset:18432
	ds_read_b128 v[60:63], v246 offset:19456
	s_add_i32 m0, s33, 0xc000
	ds_read_b128 v[160:163], v193
	ds_read_b128 v[164:167], v193 offset:1024
	ds_read_b128 v[180:183], v193 offset:2048
	ds_read_b128 v[184:187], v193 offset:3072
	ds_read_b128 v[188:191], v193 offset:4096
	ds_read_b128 v[194:197], v193 offset:5120
	ds_read_b128 v[198:201], v193 offset:6144
	ds_read_b128 v[202:205], v193 offset:7168
	global_load_lds_dwordx4 v176, s[6:7]
	s_add_i32 m0, s33, 0xe000
	s_add_u32 s10, s86, 0x8000
	s_addc_u32 s11, s87, 0
	global_load_lds_dwordx4 v178, s[6:7]
	s_waitcnt vmcnt(8) lgkmcnt(0)
	s_barrier
	v_mfma_f32_16x16x32_bf16 v[156:159], v[16:19], v[160:163], v[156:159]
	v_mfma_f32_16x16x32_bf16 v[152:155], v[24:27], v[160:163], v[152:155]
	v_mfma_f32_16x16x32_bf16 v[140:143], v[16:19], v[180:183], v[140:143]
	v_mfma_f32_16x16x32_bf16 v[136:139], v[24:27], v[180:183], v[136:139]
	v_mfma_f32_16x16x32_bf16 v[124:127], v[16:19], v[188:191], v[124:127]
	v_mfma_f32_16x16x32_bf16 v[120:123], v[24:27], v[188:191], v[120:123]
	v_mfma_f32_16x16x32_bf16 v[108:111], v[16:19], v[198:201], v[108:111]
	v_mfma_f32_16x16x32_bf16 v[104:107], v[24:27], v[198:201], v[104:107]
	v_mfma_f32_16x16x32_bf16 v[156:159], v[20:23], v[164:167], v[156:159]
	v_mfma_f32_16x16x32_bf16 v[152:155], v[32:35], v[164:167], v[152:155]
	v_mfma_f32_16x16x32_bf16 v[140:143], v[20:23], v[184:187], v[140:143]
	v_mfma_f32_16x16x32_bf16 v[136:139], v[32:35], v[184:187], v[136:139]
	v_mfma_f32_16x16x32_bf16 v[124:127], v[20:23], v[194:197], v[124:127]
	v_mfma_f32_16x16x32_bf16 v[120:123], v[32:35], v[194:197], v[120:123]
	v_mfma_f32_16x16x32_bf16 v[108:111], v[20:23], v[202:205], v[108:111]
	v_mfma_f32_16x16x32_bf16 v[104:107], v[32:35], v[202:205], v[104:107]
	v_mfma_f32_16x16x32_bf16 v[148:151], v[48:51], v[160:163], v[148:151]
	v_mfma_f32_16x16x32_bf16 v[144:147], v[56:59], v[160:163], v[144:147]
	v_mfma_f32_16x16x32_bf16 v[132:135], v[48:51], v[180:183], v[132:135]
	v_mfma_f32_16x16x32_bf16 v[128:131], v[56:59], v[180:183], v[128:131]
	v_mfma_f32_16x16x32_bf16 v[116:119], v[48:51], v[188:191], v[116:119]
	v_mfma_f32_16x16x32_bf16 v[112:115], v[56:59], v[188:191], v[112:115]
	v_mfma_f32_16x16x32_bf16 v[100:103], v[48:51], v[198:201], v[100:103]
	v_mfma_f32_16x16x32_bf16 v[96:99], v[56:59], v[198:201], v[96:99]
	v_mfma_f32_16x16x32_bf16 v[148:151], v[52:55], v[164:167], v[148:151]
	v_mfma_f32_16x16x32_bf16 v[144:147], v[60:63], v[164:167], v[144:147]
	v_mfma_f32_16x16x32_bf16 v[132:135], v[52:55], v[184:187], v[132:135]
	v_mfma_f32_16x16x32_bf16 v[128:131], v[60:63], v[184:187], v[128:131]
	v_mfma_f32_16x16x32_bf16 v[116:119], v[52:55], v[194:197], v[116:119]
	v_mfma_f32_16x16x32_bf16 v[112:115], v[60:63], v[194:197], v[112:115]
	v_mfma_f32_16x16x32_bf16 v[100:103], v[52:55], v[202:205], v[100:103]
	v_mfma_f32_16x16x32_bf16 v[96:99], v[60:63], v[202:205], v[96:99]
	s_barrier
; #define PG8_STAGE(bufoff, gbase, voff) do { _Pragma("unroll") for (int _i = 0; _i < 2; ++_i) \
;         __builtin_amdgcn_global_load_lds((const unsigned*)((const char*)(gbase) + (voff)[_i]), (PG8_LAS unsigned*)(lds + (bufoff) + ldsw + _i * 8192), 16, 0, 0); } while (0)
; #define PG8_LDA(dst, b, h) do { _Pragma("unroll") for (int m = 0; m < 4; ++m) _Pragma("unroll") for (int k = 0; k < 2; ++k) dst[m][k] = *(const PG8_LAS bf16x8*)(lds + PG8_SA(b, h) + aoff + m * 2048 + k * 1024); } while (0)
; #define PG8_LDB(dst, b, h) do { _Pragma("unroll") for (int n = 0; n < 2; ++n) _Pragma("unroll") for (int k = 0; k < 2; ++k) dst[n][k] = *(const PG8_LAS bf16x8*)(lds + PG8_SB(b, h) + boff + n * 2048 + k * 1024); } while (0)
; #define PG8_MMA(ai, bj, At, Bt) do { __builtin_amdgcn_s_setprio(1); _Pragma("unroll") for (int m = 0; m < 4; ++m) _Pragma("unroll") for (int n = 0; n < 2; ++n) _Pragma("unroll") for (int k = 0; k < 2; ++k) \
;         acc[ai][bj][m][n] = __builtin_amdgcn_mfma_f32_16x16x32_bf16(Bt[n][k], At[m][k], acc[ai][bj][m][n], 0, 0, 0); __builtin_amdgcn_s_setprio(0); } while (0)
; #define PG8_WAIT_V(n) asm volatile("s_waitcnt vmcnt(" #n ")" ::: "memory")
; #define PG8_WAIT_L(n) asm volatile("s_waitcnt lgkmcnt(" #n ")" ::: "memory")
; #define PG8_BAR __builtin_amdgcn_s_barrier()
; #define PG8_SCHED __builtin_amdgcn_sched_barrier(0)
; template <class Epi, class Sched, bool ALIGN_EPI = false, bool SP2 = false>
; __device__ __forceinline__ void gemm_phase(PG8_LAS unsigned char* lds, const Gemm g, const Sched& S, const Epi& E) {
;     ...
;             PG8_WAIT_V(8); PG8_WAIT_L(0); PG8_BAR; PG8_MMA(0, 0, At, B0); PG8_MMA(0, 1, At, B1); PG8_BAR; PG8_SCHED;
;             PG8_LDA(At, 0, 1); PG8_STAGE(PG8_SB(0, 0), b2, voffB); PG8_STAGE(PG8_SB(0, 1), b2 + hstep, voffB); PG8_STAGE(PG8_SA(0, 0), a2, voffA);
;             PG8_WAIT_V(8); PG8_WAIT_L(0); PG8_BAR; PG8_MMA(1, 0, At, B0); PG8_MMA(1, 1, At, B1); PG8_BAR; PG8_SCHED;
;             PG8_LDB(B0, 1, 0); PG8_LDB(B1, 1, 1); PG8_SCHED; PG8_LDA(At, 1, 0); PG8_STAGE(PG8_SA(0, 1), a2 + hstep, voffA);
	s_add_i32 m0, s57, 0x10000
	ds_read_b128 v[160:163], v193 offset:16384
	ds_read_b128 v[164:167], v193 offset:17408
	ds_read_b128 v[180:183], v193 offset:18432
	ds_read_b128 v[184:187], v193 offset:19456
	ds_read_b128 v[188:191], v193 offset:20480
	ds_read_b128 v[194:197], v193 offset:21504
	ds_read_b128 v[198:201], v193 offset:22528
	ds_read_b128 v[202:205], v193 offset:23552
	global_load_lds_dwordx4 v170, s[84:85]
	s_add_i32 m0, s57, 0x12000
	s_add_u32 s88, s84, 0x4000
	s_addc_u32 s89, s85, 0
	global_load_lds_dwordx4 v174, s[84:85]
	s_add_i32 m0, s57, 0x14000
	s_add_u32 s6, s6, 0x10000
	s_addc_u32 s7, s7, 0
	global_load_lds_dwordx4 v170, s[88:89]
	s_add_i32 m0, s57, 0x16000
	s_add_u32 s30, s30, 0x10000
	s_addc_u32 s37, s37, 0
	global_load_lds_dwordx4 v174, s[88:89]
	s_mov_b32 m0, s33
	s_nop 0
	global_load_lds_dwordx4 v168, s[86:87]
	s_mov_b32 m0, s42
	s_nop 0
	global_load_lds_dwordx4 v172, s[86:87]
	s_waitcnt vmcnt(8) lgkmcnt(0)
	s_barrier
	v_mfma_f32_16x16x32_bf16 v[92:95], v[16:19], v[160:163], v[92:95]
	v_mfma_f32_16x16x32_bf16 v[88:91], v[24:27], v[160:163], v[88:91]
	v_mfma_f32_16x16x32_bf16 v[76:79], v[16:19], v[180:183], v[76:79]
	v_mfma_f32_16x16x32_bf16 v[72:75], v[24:27], v[180:183], v[72:75]
	v_mfma_f32_16x16x32_bf16 v[44:47], v[16:19], v[188:191], v[44:47]
	v_mfma_f32_16x16x32_bf16 v[40:43], v[24:27], v[188:191], v[40:43]
	v_mfma_f32_16x16x32_bf16 v[12:15], v[16:19], v[198:201], v[12:15]
	v_mfma_f32_16x16x32_bf16 v[8:11], v[24:27], v[198:201], v[8:11]
	v_mfma_f32_16x16x32_bf16 v[92:95], v[20:23], v[164:167], v[92:95]
	v_mfma_f32_16x16x32_bf16 v[88:91], v[32:35], v[164:167], v[88:91]
	v_mfma_f32_16x16x32_bf16 v[76:79], v[20:23], v[184:187], v[76:79]
	v_mfma_f32_16x16x32_bf16 v[72:75], v[32:35], v[184:187], v[72:75]
	v_mfma_f32_16x16x32_bf16 v[44:47], v[20:23], v[194:197], v[44:47]
	v_mfma_f32_16x16x32_bf16 v[40:43], v[32:35], v[194:197], v[40:43]
	v_mfma_f32_16x16x32_bf16 v[12:15], v[20:23], v[202:205], v[12:15]
	v_mfma_f32_16x16x32_bf16 v[8:11], v[32:35], v[202:205], v[8:11]
	v_mfma_f32_16x16x32_bf16 v[36:39], v[48:51], v[188:191], v[36:39]
	v_mfma_f32_16x16x32_bf16 v[28:31], v[56:59], v[188:191], v[28:31]
	v_mfma_f32_16x16x32_bf16 v[4:7], v[48:51], v[198:201], v[4:7]
	v_mfma_f32_16x16x32_bf16 v[0:3], v[56:59], v[198:201], v[0:3]
	v_mfma_f32_16x16x32_bf16 v[16:19], v[48:51], v[160:163], v[84:87]
	v_mfma_f32_16x16x32_bf16 v[20:23], v[56:59], v[160:163], v[80:83]
	v_mfma_f32_16x16x32_bf16 v[24:27], v[48:51], v[180:183], v[68:71]
	v_mfma_f32_16x16x32_bf16 v[32:35], v[56:59], v[180:183], v[64:67]
	v_mfma_f32_16x16x32_bf16 v[36:39], v[52:55], v[194:197], v[36:39]
	v_mfma_f32_16x16x32_bf16 v[28:31], v[60:63], v[194:197], v[28:31]
	v_mfma_f32_16x16x32_bf16 v[4:7], v[52:55], v[202:205], v[4:7]
	v_mfma_f32_16x16x32_bf16 v[0:3], v[60:63], v[202:205], v[0:3]
	v_mfma_f32_16x16x32_bf16 v[16:19], v[52:55], v[164:167], v[16:19]
	v_mfma_f32_16x16x32_bf16 v[20:23], v[60:63], v[164:167], v[20:23]
	v_mfma_f32_16x16x32_bf16 v[24:27], v[52:55], v[184:187], v[24:27]
	v_mfma_f32_16x16x32_bf16 v[32:35], v[60:63], v[184:187], v[32:35]
	s_barrier
	ds_read_b128 v[48:51], v246 offset:32768
	ds_read_b128 v[52:55], v246 offset:33792
	ds_read_b128 v[56:59], v246 offset:34816
	ds_read_b128 v[60:63], v246 offset:35840
	ds_read_b128 v[160:163], v246 offset:49152
	ds_read_b128 v[164:167], v246 offset:50176
	ds_read_b128 v[180:183], v246 offset:51200
	ds_read_b128 v[184:187], v246 offset:52224
	s_add_u32 s86, s86, 0x4000
	s_addc_u32 s87, s87, 0
	s_mov_b32 m0, s64
	ds_read_b128 v[64:67], v193 offset:32768
	ds_read_b128 v[68:71], v193 offset:33792
	ds_read_b128 v[80:83], v193 offset:34816
	ds_read_b128 v[84:87], v193 offset:35840
	ds_read_b128 v[188:191], v193 offset:36864
	ds_read_b128 v[194:197], v193 offset:37888
	ds_read_b128 v[198:201], v193 offset:38912
	ds_read_b128 v[202:205], v193 offset:39936
	global_load_lds_dwordx4 v168, s[86:87]
	s_mov_b32 m0, s65
	s_nop 0
	global_load_lds_dwordx4 v172, s[86:87]
	s_waitcnt vmcnt(8) lgkmcnt(0)
	s_barrier
; #define PG8_STAGE(bufoff, gbase, voff) do { _Pragma("unroll") for (int _i = 0; _i < 2; ++_i) \
;         __builtin_amdgcn_global_load_lds((const unsigned*)((const char*)(gbase) + (voff)[_i]), (PG8_LAS unsigned*)(lds + (bufoff) + ldsw + _i * 8192), 16, 0, 0); } while (0)
; #define PG8_LDA(dst, b, h) do { _Pragma("unroll") for (int m = 0; m < 4; ++m) _Pragma("unroll") for (int k = 0; k < 2; ++k) dst[m][k] = *(const PG8_LAS bf16x8*)(lds + PG8_SA(b, h) + aoff + m * 2048 + k * 1024); } while (0)
; #define PG8_MMA(ai, bj, At, Bt) do { __builtin_amdgcn_s_setprio(1); _Pragma("unroll") for (int m = 0; m < 4; ++m) _Pragma("unroll") for (int n = 0; n < 2; ++n) _Pragma("unroll") for (int k = 0; k < 2; ++k) \
;         acc[ai][bj][m][n] = __builtin_amdgcn_mfma_f32_16x16x32_bf16(Bt[n][k], At[m][k], acc[ai][bj][m][n], 0, 0, 0); __builtin_amdgcn_s_setprio(0); } while (0)
; #define PG8_WAIT_V(n) asm volatile("s_waitcnt vmcnt(" #n ")" ::: "memory")
; #define PG8_WAIT_L(n) asm volatile("s_waitcnt lgkmcnt(" #n ")" ::: "memory")
; #define PG8_BAR __builtin_amdgcn_s_barrier()
; #define PG8_SCHED __builtin_amdgcn_sched_barrier(0)
; template <class Epi, class Sched, bool ALIGN_EPI = false, bool SP2 = false>
; __device__ __forceinline__ void gemm_phase(PG8_LAS unsigned char* lds, const Gemm g, const Sched& S, const Epi& E) {
;     ...
;             PG8_WAIT_V(8); PG8_WAIT_L(0); PG8_BAR; PG8_MMA(0, 0, At, B0); PG8_MMA(0, 1, At, B1); PG8_BAR; PG8_SCHED;
;             PG8_LDA(At, 1, 1); PG8_STAGE(PG8_SB(1, 0), b3, voffB); PG8_STAGE(PG8_SB(1, 1), b3 + hstep, voffB); PG8_STAGE(PG8_SA(1, 0), a3, voffA);
;             PG8_WAIT_V(8); PG8_WAIT_L(0); PG8_BAR; PG8_MMA(1, 0, At, B0); PG8_MMA(1, 1, At, B1); PG8_BAR; PG8_SCHED;
;     ...
;         if constexpr (ALIGN_EPI) { if (wr == 0) PG8_BAR; }
	v_mfma_f32_16x16x32_bf16 v[156:159], v[48:51], v[64:67], v[156:159]
	v_mfma_f32_16x16x32_bf16 v[152:155], v[56:59], v[64:67], v[152:155]
	v_mfma_f32_16x16x32_bf16 v[140:143], v[48:51], v[80:83], v[140:143]
	v_mfma_f32_16x16x32_bf16 v[136:139], v[56:59], v[80:83], v[136:139]
	v_mfma_f32_16x16x32_bf16 v[124:127], v[48:51], v[188:191], v[124:127]
	v_mfma_f32_16x16x32_bf16 v[120:123], v[56:59], v[188:191], v[120:123]
	v_mfma_f32_16x16x32_bf16 v[108:111], v[48:51], v[198:201], v[108:111]
	v_mfma_f32_16x16x32_bf16 v[104:107], v[56:59], v[198:201], v[104:107]
	v_mfma_f32_16x16x32_bf16 v[156:159], v[52:55], v[68:71], v[156:159]
	v_mfma_f32_16x16x32_bf16 v[152:155], v[60:63], v[68:71], v[152:155]
	v_mfma_f32_16x16x32_bf16 v[140:143], v[52:55], v[84:87], v[140:143]
	v_mfma_f32_16x16x32_bf16 v[136:139], v[60:63], v[84:87], v[136:139]
	v_mfma_f32_16x16x32_bf16 v[124:127], v[52:55], v[194:197], v[124:127]
	v_mfma_f32_16x16x32_bf16 v[120:123], v[60:63], v[194:197], v[120:123]
	v_mfma_f32_16x16x32_bf16 v[108:111], v[52:55], v[202:205], v[108:111]
	v_mfma_f32_16x16x32_bf16 v[104:107], v[60:63], v[202:205], v[104:107]
	v_mfma_f32_16x16x32_bf16 v[148:151], v[160:163], v[64:67], v[148:151]
	v_mfma_f32_16x16x32_bf16 v[64:67], v[180:183], v[64:67], v[144:147]
	v_mfma_f32_16x16x32_bf16 v[144:147], v[184:187], v[68:71], v[64:67]
	v_mfma_f32_16x16x32_bf16 v[64:67], v[160:163], v[80:83], v[132:135]
	v_mfma_f32_16x16x32_bf16 v[132:135], v[164:167], v[84:87], v[64:67]
	v_mfma_f32_16x16x32_bf16 v[64:67], v[180:183], v[80:83], v[128:131]
	v_mfma_f32_16x16x32_bf16 v[128:131], v[184:187], v[84:87], v[64:67]
	v_mfma_f32_16x16x32_bf16 v[64:67], v[160:163], v[188:191], v[116:119]
	v_mfma_f32_16x16x32_bf16 v[116:119], v[164:167], v[194:197], v[64:67]
	v_mfma_f32_16x16x32_bf16 v[64:67], v[180:183], v[188:191], v[112:115]
	v_mfma_f32_16x16x32_bf16 v[112:115], v[184:187], v[194:197], v[64:67]
	v_mfma_f32_16x16x32_bf16 v[64:67], v[160:163], v[198:201], v[100:103]
	v_mfma_f32_16x16x32_bf16 v[100:103], v[164:167], v[202:205], v[64:67]
	v_mfma_f32_16x16x32_bf16 v[64:67], v[180:183], v[198:201], v[96:99]
	v_mfma_f32_16x16x32_bf16 v[148:151], v[164:167], v[68:71], v[148:151]
	v_mfma_f32_16x16x32_bf16 v[96:99], v[184:187], v[202:205], v[64:67]
	s_barrier
	s_add_u32 s86, s84, 0x8000
	s_addc_u32 s87, s85, 0
	s_add_i32 m0, s57, 0x18000
	ds_read_b128 v[64:67], v193 offset:49152
	ds_read_b128 v[68:71], v193 offset:50176
	ds_read_b128 v[188:191], v193 offset:51200
	ds_read_b128 v[194:197], v193 offset:52224
	ds_read_b128 v[198:201], v193 offset:53248
	ds_read_b128 v[202:205], v193 offset:54272
	ds_read_b128 v[206:209], v193 offset:55296
	ds_read_b128 v[210:213], v193 offset:56320
	global_load_lds_dwordx4 v170, s[86:87]
	s_add_i32 m0, s57, 0x1a000
	s_add_u32 s84, s84, 0xc000
	s_addc_u32 s85, s85, 0
	global_load_lds_dwordx4 v174, s[86:87]
	s_add_i32 m0, s57, 0x1c000
	s_nop 0
	global_load_lds_dwordx4 v170, s[84:85]
	s_add_i32 m0, s57, 0x1e000
	s_nop 0
	global_load_lds_dwordx4 v174, s[84:85]
	s_mov_b32 m0, s53
	s_nop 0
	global_load_lds_dwordx4 v168, s[10:11]
	s_mov_b32 m0, s27
	s_nop 0
	global_load_lds_dwordx4 v172, s[10:11]
	s_waitcnt vmcnt(8) lgkmcnt(0)
	s_barrier
	v_mfma_f32_16x16x32_bf16 v[80:83], v[48:51], v[64:67], v[92:95]
	v_mfma_f32_16x16x32_bf16 v[92:95], v[52:55], v[68:71], v[80:83]
	v_mfma_f32_16x16x32_bf16 v[80:83], v[56:59], v[64:67], v[88:91]
	v_mfma_f32_16x16x32_bf16 v[76:79], v[48:51], v[188:191], v[76:79]
	v_mfma_f32_16x16x32_bf16 v[72:75], v[56:59], v[188:191], v[72:75]
	v_mfma_f32_16x16x32_bf16 v[44:47], v[48:51], v[198:201], v[44:47]
	v_mfma_f32_16x16x32_bf16 v[40:43], v[56:59], v[198:201], v[40:43]
	v_mfma_f32_16x16x32_bf16 v[12:15], v[48:51], v[206:209], v[12:15]
	v_mfma_f32_16x16x32_bf16 v[8:11], v[56:59], v[206:209], v[8:11]
	v_mfma_f32_16x16x32_bf16 v[88:91], v[60:63], v[68:71], v[80:83]
	v_mfma_f32_16x16x32_bf16 v[76:79], v[52:55], v[194:197], v[76:79]
	v_mfma_f32_16x16x32_bf16 v[72:75], v[60:63], v[194:197], v[72:75]
	v_mfma_f32_16x16x32_bf16 v[44:47], v[52:55], v[202:205], v[44:47]
	v_mfma_f32_16x16x32_bf16 v[40:43], v[60:63], v[202:205], v[40:43]
	v_mfma_f32_16x16x32_bf16 v[12:15], v[52:55], v[210:213], v[12:15]
	v_mfma_f32_16x16x32_bf16 v[8:11], v[60:63], v[210:213], v[8:11]
	v_mfma_f32_16x16x32_bf16 v[16:19], v[160:163], v[64:67], v[16:19]
	v_mfma_f32_16x16x32_bf16 v[84:87], v[164:167], v[68:71], v[16:19]
	v_mfma_f32_16x16x32_bf16 v[16:19], v[180:183], v[64:67], v[20:23]
	v_mfma_f32_16x16x32_bf16 v[80:83], v[184:187], v[68:71], v[16:19]
	v_mfma_f32_16x16x32_bf16 v[16:19], v[160:163], v[188:191], v[24:27]
	v_mfma_f32_16x16x32_bf16 v[68:71], v[164:167], v[194:197], v[16:19]
	v_mfma_f32_16x16x32_bf16 v[16:19], v[180:183], v[188:191], v[32:35]
	v_mfma_f32_16x16x32_bf16 v[64:67], v[184:187], v[194:197], v[16:19]
	v_mfma_f32_16x16x32_bf16 v[16:19], v[160:163], v[198:201], v[36:39]
	v_mfma_f32_16x16x32_bf16 v[36:39], v[164:167], v[202:205], v[16:19]
	v_mfma_f32_16x16x32_bf16 v[16:19], v[180:183], v[198:201], v[28:31]
	v_mfma_f32_16x16x32_bf16 v[4:7], v[160:163], v[206:209], v[4:7]
	v_mfma_f32_16x16x32_bf16 v[0:3], v[180:183], v[206:209], v[0:3]
	v_mfma_f32_16x16x32_bf16 v[28:31], v[184:187], v[202:205], v[16:19]
	v_mfma_f32_16x16x32_bf16 v[4:7], v[164:167], v[210:213], v[4:7]
	v_mfma_f32_16x16x32_bf16 v[0:3], v[184:187], v[210:213], v[0:3]
	s_barrier
	s_add_i32 s40, s40, 2
	s_cmp_gt_u32 s40, 13
	s_cbranch_scc0 .LBB0_1130
	s_and_b64 vcc, exec, s[70:71]
	s_cbranch_vccz .LBB0_1133
	s_barrier

; #define PG8_STAGE(bufoff, gbase, voff) do { _Pragma("unroll") for (int _i = 0; _i < 2; ++_i) \
;         __builtin_amdgcn_global_load_lds((const unsigned*)((const char*)(gbase) + (voff)[_i]), (PG8_LAS unsigned*)(lds + (bufoff) + ldsw + _i * 8192), 16, 0, 0); } while (0)
; #define PG8_LDA(dst, b, h) do { _Pragma("unroll") for (int m = 0; m < 4; ++m) _Pragma("unroll") for (int k = 0; k < 2; ++k) dst[m][k] = *(const PG8_LAS bf16x8*)(lds + PG8_SA(b, h) + aoff + m * 2048 + k * 1024); } while (0)
; #define PG8_LDB(dst, b, h) do { _Pragma("unroll") for (int n = 0; n < 2; ++n) _Pragma("unroll") for (int k = 0; k < 2; ++k) dst[n][k] = *(const PG8_LAS bf16x8*)(lds + PG8_SB(b, h) + boff + n * 2048 + k * 1024); } while (0)
; #define PG8_WAIT_V(n) asm volatile("s_waitcnt vmcnt(" #n ")" ::: "memory")
; #define PG8_WAIT_L(n) asm volatile("s_waitcnt lgkmcnt(" #n ")" ::: "memory")
; #define PG8_BAR __builtin_amdgcn_s_barrier()
; #define PG8_SCHED __builtin_amdgcn_sched_barrier(0)
; template <class Epi, class Sched, bool ALIGN_EPI = false, bool SP2 = false>
; __device__ __forceinline__ void gemm_phase(PG8_LAS unsigned char* lds, const Gemm g, const Sched& S, const Epi& E) {
;     ...
;         const bool has_next = S.next(ui + 1, nxt);
;         const char* nA = has_next ? (const char*)g.A + (size_t)nxt.pm * tstep : cA; const char* nB = has_next ? (const char*)g.Bt + (size_t)nxt.pn * tstep : cB;
;         for (int t = 0; t < nt; t += 2) {
;             const bool last = (t == nt - 2);
;             const char* a1 = cA + (size_t)(t + 1) * kstep;
;             const char* a2 = last ? nA : cA + (size_t)(t + 2) * kstep; const char* b2 = last ? nB : cB + (size_t)(t + 2) * kstep;
;             const char* a3 = a2 + kstep; const char* b3 = b2 + kstep;
;             if (last && has_next) S.a_ready(nxt);
;             if constexpr (SP2) {
;             PG8_LDB(B0, 0, 0); PG8_LDB(B1, 0, 1); PG8_SCHED; PG8_LDA(At, 0, 0); PG8_STAGE(PG8_SA(1, 1), a1 + hstep, voffA);
;             PG8_WAIT_V(8); PG8_WAIT_L(0); PG8_BAR; PG8_MMA(0, 0, At, B0); PG8_MMA(0, 1, At, B1); PG8_BAR; PG8_SCHED;
;             PG8_LDA(At, 0, 1); PG8_STAGE(PG8_SB(0, 0), b2, voffB); PG8_STAGE(PG8_SB(0, 1), b2 + hstep, voffB); PG8_STAGE(PG8_SA(0, 0), a2, voffA);
;             PG8_WAIT_V(8); PG8_WAIT_L(0); PG8_BAR; PG8_MMA(1, 0, At, B0); PG8_MMA(1, 1, At, B1); PG8_BAR; PG8_SCHED;
.LBB0_1321:
	s_add_u32 s16, s16, 0xc000
	s_addc_u32 s17, s17, 0
	s_add_u32 s66, s18, 0x10000
	v_mov_b32_e32 v0, 0
	s_addc_u32 s67, s19, 0
	s_mov_b32 s18, 0
	v_add_u32_e32 v246, 0x10000, v206
	s_add_i32 s75, s18, 2
	s_add_u32 s19, s16, 0x4000
	s_addc_u32 s20, s17, 0
	s_cmp_eq_u32 s59, s18
	s_cselect_b32 s64, s0, s19
	s_cselect_b32 s65, s1, s20
	s_cselect_b32 s20, s14, s66
	s_cselect_b32 s21, s15, s67
	ds_read_b128 v[80:83], v246
	ds_read_b128 v[84:87], v246 offset:1024
	ds_read_b128 v[104:107], v246 offset:2048
	ds_read_b128 v[108:111], v246 offset:3072
	ds_read_b128 v[128:131], v246 offset:16384
	ds_read_b128 v[136:139], v246 offset:17408
	ds_read_b128 v[152:155], v246 offset:18432
	ds_read_b128 v[156:159], v246 offset:19456
	s_add_i32 m0, s41, 0xc000
	ds_read_b128 v[160:163], v207
	ds_read_b128 v[164:167], v207 offset:1024
	ds_read_b128 v[168:171], v207 offset:2048
	ds_read_b128 v[172:175], v207 offset:3072
	ds_read_b128 v[176:179], v207 offset:4096
	ds_read_b128 v[180:183], v207 offset:5120
	ds_read_b128 v[198:201], v207 offset:6144
	ds_read_b128 v[202:205], v207 offset:7168
	global_load_lds_dwordx4 v194, s[16:17]
	s_add_i32 m0, s41, 0xe000
	s_add_u32 s18, s64, 0x8000
	s_addc_u32 s19, s65, 0
	global_load_lds_dwordx4 v196, s[16:17]
	s_waitcnt vmcnt(8) lgkmcnt(0)
	s_barrier
	v_mfma_f32_16x16x32_bf16 v[148:151], v[80:83], v[160:163], 0
	v_mfma_f32_16x16x32_bf16 v[144:147], v[104:107], v[160:163], 0
	v_mfma_f32_16x16x32_bf16 v[124:127], v[80:83], v[168:171], 0
	v_mfma_f32_16x16x32_bf16 v[120:123], v[104:107], v[168:171], 0
	v_mfma_f32_16x16x32_bf16 v[100:103], v[80:83], v[176:179], 0
	v_mfma_f32_16x16x32_bf16 v[96:99], v[104:107], v[176:179], 0
	v_mfma_f32_16x16x32_bf16 v[76:79], v[80:83], v[198:201], 0
	v_mfma_f32_16x16x32_bf16 v[72:75], v[104:107], v[198:201], 0
	v_mfma_f32_16x16x32_bf16 v[148:151], v[84:87], v[164:167], v[148:151]
	v_mfma_f32_16x16x32_bf16 v[144:147], v[108:111], v[164:167], v[144:147]
	v_mfma_f32_16x16x32_bf16 v[124:127], v[84:87], v[172:175], v[124:127]
	v_mfma_f32_16x16x32_bf16 v[120:123], v[108:111], v[172:175], v[120:123]
	v_mfma_f32_16x16x32_bf16 v[100:103], v[84:87], v[180:183], v[100:103]
	v_mfma_f32_16x16x32_bf16 v[96:99], v[108:111], v[180:183], v[96:99]
	v_mfma_f32_16x16x32_bf16 v[76:79], v[84:87], v[202:205], v[76:79]
	v_mfma_f32_16x16x32_bf16 v[72:75], v[108:111], v[202:205], v[72:75]
	v_mfma_f32_16x16x32_bf16 v[140:143], v[128:131], v[160:163], 0
	v_mfma_f32_16x16x32_bf16 v[132:135], v[152:155], v[160:163], 0
	v_mfma_f32_16x16x32_bf16 v[116:119], v[128:131], v[168:171], 0
	v_mfma_f32_16x16x32_bf16 v[112:115], v[152:155], v[168:171], 0
	v_mfma_f32_16x16x32_bf16 v[92:95], v[128:131], v[176:179], 0
	v_mfma_f32_16x16x32_bf16 v[88:91], v[152:155], v[176:179], 0
	v_mfma_f32_16x16x32_bf16 v[68:71], v[128:131], v[198:201], 0
	v_mfma_f32_16x16x32_bf16 v[64:67], v[152:155], v[198:201], 0
	v_mfma_f32_16x16x32_bf16 v[140:143], v[136:139], v[164:167], v[140:143]
	v_mfma_f32_16x16x32_bf16 v[132:135], v[156:159], v[164:167], v[132:135]
	v_mfma_f32_16x16x32_bf16 v[116:119], v[136:139], v[172:175], v[116:119]
	v_mfma_f32_16x16x32_bf16 v[112:115], v[156:159], v[172:175], v[112:115]
	v_mfma_f32_16x16x32_bf16 v[92:95], v[136:139], v[180:183], v[92:95]
	v_mfma_f32_16x16x32_bf16 v[88:91], v[156:159], v[180:183], v[88:91]
	v_mfma_f32_16x16x32_bf16 v[68:71], v[136:139], v[202:205], v[68:71]
	v_mfma_f32_16x16x32_bf16 v[64:67], v[156:159], v[202:205], v[64:67]
	s_barrier
	s_add_i32 m0, s39, 0x10000
	ds_read_b128 v[160:163], v207 offset:16384
	ds_read_b128 v[164:167], v207 offset:17408
	ds_read_b128 v[168:171], v207 offset:18432
	ds_read_b128 v[172:175], v207 offset:19456
	ds_read_b128 v[176:179], v207 offset:20480
	ds_read_b128 v[180:183], v207 offset:21504
	ds_read_b128 v[198:201], v207 offset:22528
	ds_read_b128 v[202:205], v207 offset:23552
	global_load_lds_dwordx4 v186, s[20:21]
	s_add_i32 m0, s39, 0x12000
	s_add_u32 s76, s20, 0x4000
	s_addc_u32 s77, s21, 0
	global_load_lds_dwordx4 v190, s[20:21]
	s_add_i32 m0, s39, 0x14000
	s_add_u32 s16, s16, 0x10000
	s_addc_u32 s17, s17, 0
	global_load_lds_dwordx4 v186, s[76:77]
	s_add_i32 m0, s39, 0x16000
	s_add_u32 s66, s66, 0x10000
	s_addc_u32 s67, s67, 0
	global_load_lds_dwordx4 v190, s[76:77]
	s_mov_b32 m0, s41
	s_nop 0
	global_load_lds_dwordx4 v184, s[64:65]
	s_mov_b32 m0, s42
	s_nop 0
	global_load_lds_dwordx4 v188, s[64:65]
	s_waitcnt vmcnt(8) lgkmcnt(0)
	s_barrier
	v_mfma_f32_16x16x32_bf16 v[60:63], v[80:83], v[160:163], 0
	v_mfma_f32_16x16x32_bf16 v[56:59], v[104:107], v[160:163], 0
	v_mfma_f32_16x16x32_bf16 v[44:47], v[80:83], v[168:171], 0
	v_mfma_f32_16x16x32_bf16 v[40:43], v[104:107], v[168:171], 0
	v_mfma_f32_16x16x32_bf16 v[28:31], v[80:83], v[176:179], 0
	v_mfma_f32_16x16x32_bf16 v[24:27], v[104:107], v[176:179], 0
	v_mfma_f32_16x16x32_bf16 v[12:15], v[80:83], v[198:201], 0
	v_mfma_f32_16x16x32_bf16 v[8:11], v[104:107], v[198:201], 0
	v_mfma_f32_16x16x32_bf16 v[60:63], v[84:87], v[164:167], v[60:63]
	v_mfma_f32_16x16x32_bf16 v[56:59], v[108:111], v[164:167], v[56:59]
	v_mfma_f32_16x16x32_bf16 v[44:47], v[84:87], v[172:175], v[44:47]
	v_mfma_f32_16x16x32_bf16 v[40:43], v[108:111], v[172:175], v[40:43]
	v_mfma_f32_16x16x32_bf16 v[28:31], v[84:87], v[180:183], v[28:31]
	v_mfma_f32_16x16x32_bf16 v[24:27], v[108:111], v[180:183], v[24:27]
	v_mfma_f32_16x16x32_bf16 v[12:15], v[84:87], v[202:205], v[12:15]
	v_mfma_f32_16x16x32_bf16 v[8:11], v[108:111], v[202:205], v[8:11]
	v_mfma_f32_16x16x32_bf16 v[52:55], v[128:131], v[160:163], 0
	v_mfma_f32_16x16x32_bf16 v[48:51], v[152:155], v[160:163], 0
	v_mfma_f32_16x16x32_bf16 v[36:39], v[128:131], v[168:171], 0
	v_mfma_f32_16x16x32_bf16 v[32:35], v[152:155], v[168:171], 0
	v_mfma_f32_16x16x32_bf16 v[20:23], v[128:131], v[176:179], 0
	v_mfma_f32_16x16x32_bf16 v[16:19], v[152:155], v[176:179], 0
	v_mfma_f32_16x16x32_bf16 v[4:7], v[128:131], v[198:201], 0
	v_mfma_f32_16x16x32_bf16 v[0:3], v[152:155], v[198:201], 0
	v_mfma_f32_16x16x32_bf16 v[52:55], v[136:139], v[164:167], v[52:55]
	v_mfma_f32_16x16x32_bf16 v[48:51], v[156:159], v[164:167], v[48:51]
	v_mfma_f32_16x16x32_bf16 v[36:39], v[136:139], v[172:175], v[36:39]
	v_mfma_f32_16x16x32_bf16 v[32:35], v[156:159], v[172:175], v[32:35]
	v_mfma_f32_16x16x32_bf16 v[20:23], v[136:139], v[180:183], v[20:23]
	v_mfma_f32_16x16x32_bf16 v[16:19], v[156:159], v[180:183], v[16:19]
	v_mfma_f32_16x16x32_bf16 v[4:7], v[136:139], v[202:205], v[4:7]
	v_mfma_f32_16x16x32_bf16 v[0:3], v[156:159], v[202:205], v[0:3]
	s_barrier
; #define PG8_STAGE(bufoff, gbase, voff) do { _Pragma("unroll") for (int _i = 0; _i < 2; ++_i) \
;         __builtin_amdgcn_global_load_lds((const unsigned*)((const char*)(gbase) + (voff)[_i]), (PG8_LAS unsigned*)(lds + (bufoff) + ldsw + _i * 8192), 16, 0, 0); } while (0)
; #define PG8_LDA(dst, b, h) do { _Pragma("unroll") for (int m = 0; m < 4; ++m) _Pragma("unroll") for (int k = 0; k < 2; ++k) dst[m][k] = *(const PG8_LAS bf16x8*)(lds + PG8_SA(b, h) + aoff + m * 2048 + k * 1024); } while (0)
; #define PG8_LDB(dst, b, h) do { _Pragma("unroll") for (int n = 0; n < 2; ++n) _Pragma("unroll") for (int k = 0; k < 2; ++k) dst[n][k] = *(const PG8_LAS bf16x8*)(lds + PG8_SB(b, h) + boff + n * 2048 + k * 1024); } while (0)
; #define PG8_MMA(ai, bj, At, Bt) do { __builtin_amdgcn_s_setprio(1); _Pragma("unroll") for (int m = 0; m < 4; ++m) _Pragma("unroll") for (int n = 0; n < 2; ++n) _Pragma("unroll") for (int k = 0; k < 2; ++k) \
;         acc[ai][bj][m][n] = __builtin_amdgcn_mfma_f32_16x16x32_bf16(Bt[n][k], At[m][k], acc[ai][bj][m][n], 0, 0, 0); __builtin_amdgcn_s_setprio(0); } while (0)
; #define PG8_WAIT_V(n) asm volatile("s_waitcnt vmcnt(" #n ")" ::: "memory")
; #define PG8_WAIT_L(n) asm volatile("s_waitcnt lgkmcnt(" #n ")" ::: "memory")
; #define PG8_BAR __builtin_amdgcn_s_barrier()
; #define PG8_SCHED __builtin_amdgcn_sched_barrier(0)
; template <class Epi, class Sched, bool ALIGN_EPI = false, bool SP2 = false>
; __device__ __forceinline__ void gemm_phase(PG8_LAS unsigned char* lds, const Gemm g, const Sched& S, const Epi& E) {
;     ...
;         for (int t = 0; t < nt; t += 2) {
;     ...
;             PG8_LDB(B0, 1, 0); PG8_LDB(B1, 1, 1); PG8_SCHED; PG8_LDA(At, 1, 0); PG8_STAGE(PG8_SA(0, 1), a2 + hstep, voffA);
;             PG8_WAIT_V(8); PG8_WAIT_L(0); PG8_BAR; PG8_MMA(0, 0, At, B0); PG8_MMA(0, 1, At, B1); PG8_BAR; PG8_SCHED;
;             PG8_LDA(At, 1, 1); PG8_STAGE(PG8_SB(1, 0), b3, voffB); PG8_STAGE(PG8_SB(1, 1), b3 + hstep, voffB); PG8_STAGE(PG8_SA(1, 0), a3, voffA);
;             PG8_WAIT_V(8); PG8_WAIT_L(0); PG8_BAR; PG8_MMA(1, 0, At, B0); PG8_MMA(1, 1, At, B1); PG8_BAR; PG8_SCHED;
	ds_read_b128 v[80:83], v246 offset:32768
	ds_read_b128 v[84:87], v246 offset:33792
	ds_read_b128 v[104:107], v246 offset:34816
	ds_read_b128 v[108:111], v246 offset:35840
	ds_read_b128 v[128:131], v246 offset:49152
	ds_read_b128 v[136:139], v246 offset:50176
	ds_read_b128 v[152:155], v246 offset:51200
	ds_read_b128 v[156:159], v246 offset:52224
	s_add_u32 s64, s64, 0x4000
	s_addc_u32 s65, s65, 0
	s_mov_b32 m0, s50
	ds_read_b128 v[160:163], v207 offset:32768
	ds_read_b128 v[164:167], v207 offset:33792
	ds_read_b128 v[168:171], v207 offset:34816
	ds_read_b128 v[172:175], v207 offset:35840
	ds_read_b128 v[176:179], v207 offset:36864
	ds_read_b128 v[180:183], v207 offset:37888
	ds_read_b128 v[198:201], v207 offset:38912
	ds_read_b128 v[202:205], v207 offset:39936
	global_load_lds_dwordx4 v184, s[64:65]
	s_mov_b32 m0, s51
	s_nop 0
	global_load_lds_dwordx4 v188, s[64:65]
	s_waitcnt vmcnt(8) lgkmcnt(0)
	s_barrier
	v_mfma_f32_16x16x32_bf16 v[148:151], v[80:83], v[160:163], v[148:151]
	v_mfma_f32_16x16x32_bf16 v[144:147], v[104:107], v[160:163], v[144:147]
	v_mfma_f32_16x16x32_bf16 v[124:127], v[80:83], v[168:171], v[124:127]
	v_mfma_f32_16x16x32_bf16 v[120:123], v[104:107], v[168:171], v[120:123]
	v_mfma_f32_16x16x32_bf16 v[100:103], v[80:83], v[176:179], v[100:103]
	v_mfma_f32_16x16x32_bf16 v[96:99], v[104:107], v[176:179], v[96:99]
	v_mfma_f32_16x16x32_bf16 v[76:79], v[80:83], v[198:201], v[76:79]
	v_mfma_f32_16x16x32_bf16 v[72:75], v[104:107], v[198:201], v[72:75]
	v_mfma_f32_16x16x32_bf16 v[148:151], v[84:87], v[164:167], v[148:151]
	v_mfma_f32_16x16x32_bf16 v[144:147], v[108:111], v[164:167], v[144:147]
	v_mfma_f32_16x16x32_bf16 v[124:127], v[84:87], v[172:175], v[124:127]
	v_mfma_f32_16x16x32_bf16 v[120:123], v[108:111], v[172:175], v[120:123]
	v_mfma_f32_16x16x32_bf16 v[100:103], v[84:87], v[180:183], v[100:103]
	v_mfma_f32_16x16x32_bf16 v[96:99], v[108:111], v[180:183], v[96:99]
	v_mfma_f32_16x16x32_bf16 v[76:79], v[84:87], v[202:205], v[76:79]
	v_mfma_f32_16x16x32_bf16 v[72:75], v[108:111], v[202:205], v[72:75]
	v_mfma_f32_16x16x32_bf16 v[140:143], v[128:131], v[160:163], v[140:143]
	v_mfma_f32_16x16x32_bf16 v[132:135], v[152:155], v[160:163], v[132:135]
	v_mfma_f32_16x16x32_bf16 v[116:119], v[128:131], v[168:171], v[116:119]
	v_mfma_f32_16x16x32_bf16 v[112:115], v[152:155], v[168:171], v[112:115]
	v_mfma_f32_16x16x32_bf16 v[92:95], v[128:131], v[176:179], v[92:95]
	v_mfma_f32_16x16x32_bf16 v[88:91], v[152:155], v[176:179], v[88:91]
	v_mfma_f32_16x16x32_bf16 v[68:71], v[128:131], v[198:201], v[68:71]
	v_mfma_f32_16x16x32_bf16 v[64:67], v[152:155], v[198:201], v[64:67]
	v_mfma_f32_16x16x32_bf16 v[140:143], v[136:139], v[164:167], v[140:143]
	v_mfma_f32_16x16x32_bf16 v[132:135], v[156:159], v[164:167], v[132:135]
	v_mfma_f32_16x16x32_bf16 v[116:119], v[136:139], v[172:175], v[116:119]
	v_mfma_f32_16x16x32_bf16 v[112:115], v[156:159], v[172:175], v[112:115]
	v_mfma_f32_16x16x32_bf16 v[92:95], v[136:139], v[180:183], v[92:95]
	v_mfma_f32_16x16x32_bf16 v[88:91], v[156:159], v[180:183], v[88:91]
	v_mfma_f32_16x16x32_bf16 v[68:71], v[136:139], v[202:205], v[68:71]
	v_mfma_f32_16x16x32_bf16 v[64:67], v[156:159], v[202:205], v[64:67]
	s_barrier
	s_add_u32 s64, s20, 0x8000
	s_addc_u32 s65, s21, 0
	s_add_i32 m0, s39, 0x18000
	ds_read_b128 v[160:163], v207 offset:49152
	ds_read_b128 v[164:167], v207 offset:50176
	ds_read_b128 v[168:171], v207 offset:51200
	ds_read_b128 v[172:175], v207 offset:52224
	ds_read_b128 v[176:179], v207 offset:53248
	ds_read_b128 v[180:183], v207 offset:54272
	ds_read_b128 v[198:201], v207 offset:55296
	ds_read_b128 v[202:205], v207 offset:56320
	global_load_lds_dwordx4 v186, s[64:65]
	s_add_i32 m0, s39, 0x1a000
	s_add_u32 s20, s20, 0xc000
	s_addc_u32 s21, s21, 0
	global_load_lds_dwordx4 v190, s[64:65]
	s_add_i32 m0, s39, 0x1c000
	s_nop 0
	global_load_lds_dwordx4 v186, s[20:21]
	s_add_i32 m0, s39, 0x1e000
	s_nop 0
	global_load_lds_dwordx4 v190, s[20:21]
	s_mov_b32 m0, s56
	s_nop 0
	global_load_lds_dwordx4 v184, s[18:19]
	s_mov_b32 m0, s57
	s_nop 0
	global_load_lds_dwordx4 v188, s[18:19]
	s_waitcnt vmcnt(8) lgkmcnt(0)
	s_barrier
	v_mfma_f32_16x16x32_bf16 v[60:63], v[80:83], v[160:163], v[60:63]
	v_mfma_f32_16x16x32_bf16 v[56:59], v[104:107], v[160:163], v[56:59]
	v_mfma_f32_16x16x32_bf16 v[44:47], v[80:83], v[168:171], v[44:47]
	v_mfma_f32_16x16x32_bf16 v[40:43], v[104:107], v[168:171], v[40:43]
	v_mfma_f32_16x16x32_bf16 v[28:31], v[80:83], v[176:179], v[28:31]
	v_mfma_f32_16x16x32_bf16 v[24:27], v[104:107], v[176:179], v[24:27]
	v_mfma_f32_16x16x32_bf16 v[12:15], v[80:83], v[198:201], v[12:15]
	v_mfma_f32_16x16x32_bf16 v[8:11], v[104:107], v[198:201], v[8:11]
	v_mfma_f32_16x16x32_bf16 v[60:63], v[84:87], v[164:167], v[60:63]
	v_mfma_f32_16x16x32_bf16 v[56:59], v[108:111], v[164:167], v[56:59]
	v_mfma_f32_16x16x32_bf16 v[44:47], v[84:87], v[172:175], v[44:47]
	v_mfma_f32_16x16x32_bf16 v[40:43], v[108:111], v[172:175], v[40:43]
	v_mfma_f32_16x16x32_bf16 v[28:31], v[84:87], v[180:183], v[28:31]
	v_mfma_f32_16x16x32_bf16 v[24:27], v[108:111], v[180:183], v[24:27]
	v_mfma_f32_16x16x32_bf16 v[12:15], v[84:87], v[202:205], v[12:15]
	v_mfma_f32_16x16x32_bf16 v[8:11], v[108:111], v[202:205], v[8:11]
	v_mfma_f32_16x16x32_bf16 v[52:55], v[128:131], v[160:163], v[52:55]
	v_mfma_f32_16x16x32_bf16 v[48:51], v[152:155], v[160:163], v[48:51]
	v_mfma_f32_16x16x32_bf16 v[36:39], v[128:131], v[168:171], v[36:39]
	v_mfma_f32_16x16x32_bf16 v[32:35], v[152:155], v[168:171], v[32:35]
	v_mfma_f32_16x16x32_bf16 v[20:23], v[128:131], v[176:179], v[20:23]
	v_mfma_f32_16x16x32_bf16 v[16:19], v[152:155], v[176:179], v[16:19]
	v_mfma_f32_16x16x32_bf16 v[4:7], v[128:131], v[198:201], v[4:7]
	v_mfma_f32_16x16x32_bf16 v[0:3], v[152:155], v[198:201], v[0:3]
	v_mfma_f32_16x16x32_bf16 v[52:55], v[136:139], v[164:167], v[52:55]
	v_mfma_f32_16x16x32_bf16 v[48:51], v[156:159], v[164:167], v[48:51]
	v_mfma_f32_16x16x32_bf16 v[36:39], v[136:139], v[172:175], v[36:39]
	v_mfma_f32_16x16x32_bf16 v[32:35], v[156:159], v[172:175], v[32:35]
	v_mfma_f32_16x16x32_bf16 v[20:23], v[136:139], v[180:183], v[20:23]
	v_mfma_f32_16x16x32_bf16 v[16:19], v[156:159], v[180:183], v[16:19]
	v_mfma_f32_16x16x32_bf16 v[4:7], v[136:139], v[202:205], v[4:7]
	v_mfma_f32_16x16x32_bf16 v[0:3], v[156:159], v[202:205], v[0:3]
	s_barrier
	s_cmp_ge_u32 s75, s53
	s_mov_b32 s18, s75
; #define PG8_STAGE(bufoff, gbase, voff) do { _Pragma("unroll") for (int _i = 0; _i < 2; ++_i) \
;         __builtin_amdgcn_global_load_lds((const unsigned*)((const char*)(gbase) + (voff)[_i]), (PG8_LAS unsigned*)(lds + (bufoff) + ldsw + _i * 8192), 16, 0, 0); } while (0)
; #define PG8_LDA(dst, b, h) do { _Pragma("unroll") for (int m = 0; m < 4; ++m) _Pragma("unroll") for (int k = 0; k < 2; ++k) dst[m][k] = *(const PG8_LAS bf16x8*)(lds + PG8_SA(b, h) + aoff + m * 2048 + k * 1024); } while (0)
; #define PG8_LDB(dst, b, h) do { _Pragma("unroll") for (int n = 0; n < 2; ++n) _Pragma("unroll") for (int k = 0; k < 2; ++k) dst[n][k] = *(const PG8_LAS bf16x8*)(lds + PG8_SB(b, h) + boff + n * 2048 + k * 1024); } while (0)
; #define PG8_MMA(ai, bj, At, Bt) do { __builtin_amdgcn_s_setprio(1); _Pragma("unroll") for (int m = 0; m < 4; ++m) _Pragma("unroll") for (int n = 0; n < 2; ++n) _Pragma("unroll") for (int k = 0; k < 2; ++k) \
;         acc[ai][bj][m][n] = __builtin_amdgcn_mfma_f32_16x16x32_bf16(Bt[n][k], At[m][k], acc[ai][bj][m][n], 0, 0, 0); __builtin_amdgcn_s_setprio(0); } while (0)
; #define PG8_WAIT_V(n) asm volatile("s_waitcnt vmcnt(" #n ")" ::: "memory")
; #define PG8_BAR __builtin_amdgcn_s_barrier()
; template <class Epi, class Sched, bool ALIGN_EPI = false, bool SP2 = false>
; __device__ __forceinline__ void gemm_phase(PG8_LAS unsigned char* lds, const Gemm g, const Sched& S, const Epi& E) {
;     ...
;         for (int t = 0; t < nt; t += 2) {
;             const bool last = (t == nt - 2);
;             const char* a1 = cA + (size_t)(t + 1) * kstep;
;             const char* a2 = last ? nA : cA + (size_t)(t + 2) * kstep; const char* b2 = last ? nB : cB + (size_t)(t + 2) * kstep;
;             const char* a3 = a2 + kstep; const char* b3 = b2 + kstep;
;             if (last && has_next) S.a_ready(nxt);
;             if constexpr (SP2) {
;             PG8_LDB(B0, 0, 0); PG8_LDB(B1, 0, 1); PG8_SCHED; PG8_LDA(At, 0, 0); PG8_STAGE(PG8_SA(1, 1), a1 + hstep, voffA);
;             PG8_WAIT_V(8); PG8_WAIT_L(0); PG8_BAR; PG8_MMA(0, 0, At, B0); PG8_MMA(0, 1, At, B1); PG8_BAR; PG8_SCHED;
;             PG8_LDA(At, 0, 1); PG8_STAGE(PG8_SB(0, 0), b2, voffB); PG8_STAGE(PG8_SB(0, 1), b2 + hstep, voffB); PG8_STAGE(PG8_SA(0, 0), a2, voffA);
;             PG8_WAIT_V(8); PG8_WAIT_L(0); PG8_BAR; PG8_MMA(1, 0, At, B0); PG8_MMA(1, 1, At, B1); PG8_BAR; PG8_SCHED;
.LBB0_1322:
	s_add_i32 s75, s18, 2
	s_add_u32 s19, s16, 0x4000
	s_addc_u32 s20, s17, 0
	s_cmp_eq_u32 s59, s18
	s_cselect_b32 s64, s0, s19
	s_cselect_b32 s65, s1, s20
	s_cselect_b32 s20, s14, s66
	s_cselect_b32 s21, s15, s67
	ds_read_b128 v[80:83], v246
	ds_read_b128 v[84:87], v246 offset:1024
	ds_read_b128 v[104:107], v246 offset:2048
	ds_read_b128 v[108:111], v246 offset:3072
	ds_read_b128 v[128:131], v246 offset:16384
	ds_read_b128 v[136:139], v246 offset:17408
	ds_read_b128 v[152:155], v246 offset:18432
	ds_read_b128 v[156:159], v246 offset:19456
	s_add_i32 m0, s41, 0xc000
	ds_read_b128 v[160:163], v207
	ds_read_b128 v[164:167], v207 offset:1024
	ds_read_b128 v[168:171], v207 offset:2048
	ds_read_b128 v[172:175], v207 offset:3072
	ds_read_b128 v[176:179], v207 offset:4096
	ds_read_b128 v[180:183], v207 offset:5120
	ds_read_b128 v[198:201], v207 offset:6144
	ds_read_b128 v[202:205], v207 offset:7168
	global_load_lds_dwordx4 v194, s[16:17]
	s_add_i32 m0, s41, 0xe000
	s_add_u32 s18, s64, 0x8000
	s_addc_u32 s19, s65, 0
	global_load_lds_dwordx4 v196, s[16:17]
	s_waitcnt vmcnt(8) lgkmcnt(0)
	s_barrier
	v_mfma_f32_16x16x32_bf16 v[148:151], v[80:83], v[160:163], v[148:151]
	v_mfma_f32_16x16x32_bf16 v[144:147], v[104:107], v[160:163], v[144:147]
	v_mfma_f32_16x16x32_bf16 v[124:127], v[80:83], v[168:171], v[124:127]
	v_mfma_f32_16x16x32_bf16 v[120:123], v[104:107], v[168:171], v[120:123]
	v_mfma_f32_16x16x32_bf16 v[100:103], v[80:83], v[176:179], v[100:103]
	v_mfma_f32_16x16x32_bf16 v[96:99], v[104:107], v[176:179], v[96:99]
	v_mfma_f32_16x16x32_bf16 v[76:79], v[80:83], v[198:201], v[76:79]
	v_mfma_f32_16x16x32_bf16 v[72:75], v[104:107], v[198:201], v[72:75]
	v_mfma_f32_16x16x32_bf16 v[148:151], v[84:87], v[164:167], v[148:151]
	v_mfma_f32_16x16x32_bf16 v[144:147], v[108:111], v[164:167], v[144:147]
	v_mfma_f32_16x16x32_bf16 v[124:127], v[84:87], v[172:175], v[124:127]
	v_mfma_f32_16x16x32_bf16 v[120:123], v[108:111], v[172:175], v[120:123]
	v_mfma_f32_16x16x32_bf16 v[100:103], v[84:87], v[180:183], v[100:103]
	v_mfma_f32_16x16x32_bf16 v[96:99], v[108:111], v[180:183], v[96:99]
	v_mfma_f32_16x16x32_bf16 v[76:79], v[84:87], v[202:205], v[76:79]
	v_mfma_f32_16x16x32_bf16 v[72:75], v[108:111], v[202:205], v[72:75]
	v_mfma_f32_16x16x32_bf16 v[140:143], v[128:131], v[160:163], v[140:143]
	v_mfma_f32_16x16x32_bf16 v[132:135], v[152:155], v[160:163], v[132:135]
	v_mfma_f32_16x16x32_bf16 v[116:119], v[128:131], v[168:171], v[116:119]
	v_mfma_f32_16x16x32_bf16 v[112:115], v[152:155], v[168:171], v[112:115]
	v_mfma_f32_16x16x32_bf16 v[92:95], v[128:131], v[176:179], v[92:95]
	v_mfma_f32_16x16x32_bf16 v[88:91], v[152:155], v[176:179], v[88:91]
	v_mfma_f32_16x16x32_bf16 v[68:71], v[128:131], v[198:201], v[68:71]
	v_mfma_f32_16x16x32_bf16 v[64:67], v[152:155], v[198:201], v[64:67]
	v_mfma_f32_16x16x32_bf16 v[140:143], v[136:139], v[164:167], v[140:143]
	v_mfma_f32_16x16x32_bf16 v[132:135], v[156:159], v[164:167], v[132:135]
	v_mfma_f32_16x16x32_bf16 v[116:119], v[136:139], v[172:175], v[116:119]
	v_mfma_f32_16x16x32_bf16 v[112:115], v[156:159], v[172:175], v[112:115]
	v_mfma_f32_16x16x32_bf16 v[92:95], v[136:139], v[180:183], v[92:95]
	v_mfma_f32_16x16x32_bf16 v[88:91], v[156:159], v[180:183], v[88:91]
	v_mfma_f32_16x16x32_bf16 v[68:71], v[136:139], v[202:205], v[68:71]
	v_mfma_f32_16x16x32_bf16 v[64:67], v[156:159], v[202:205], v[64:67]
	s_barrier
	s_add_i32 m0, s39, 0x10000
	ds_read_b128 v[160:163], v207 offset:16384
	ds_read_b128 v[164:167], v207 offset:17408
	ds_read_b128 v[168:171], v207 offset:18432
	ds_read_b128 v[172:175], v207 offset:19456
	ds_read_b128 v[176:179], v207 offset:20480
	ds_read_b128 v[180:183], v207 offset:21504
	ds_read_b128 v[198:201], v207 offset:22528
	ds_read_b128 v[202:205], v207 offset:23552
	global_load_lds_dwordx4 v186, s[20:21]
	s_add_i32 m0, s39, 0x12000
	s_add_u32 s76, s20, 0x4000
	s_addc_u32 s77, s21, 0
	global_load_lds_dwordx4 v190, s[20:21]
	s_add_i32 m0, s39, 0x14000
	s_add_u32 s16, s16, 0x10000
	s_addc_u32 s17, s17, 0
	global_load_lds_dwordx4 v186, s[76:77]
	s_add_i32 m0, s39, 0x16000
	s_add_u32 s66, s66, 0x10000
	s_addc_u32 s67, s67, 0
	global_load_lds_dwordx4 v190, s[76:77]
	s_mov_b32 m0, s41
	s_nop 0
	global_load_lds_dwordx4 v184, s[64:65]
	s_mov_b32 m0, s42
	s_nop 0
	global_load_lds_dwordx4 v188, s[64:65]
	s_waitcnt vmcnt(8) lgkmcnt(0)
	s_barrier
	v_mfma_f32_16x16x32_bf16 v[60:63], v[80:83], v[160:163], v[60:63]
	v_mfma_f32_16x16x32_bf16 v[56:59], v[104:107], v[160:163], v[56:59]
	v_mfma_f32_16x16x32_bf16 v[44:47], v[80:83], v[168:171], v[44:47]
	v_mfma_f32_16x16x32_bf16 v[40:43], v[104:107], v[168:171], v[40:43]
	v_mfma_f32_16x16x32_bf16 v[28:31], v[80:83], v[176:179], v[28:31]
	v_mfma_f32_16x16x32_bf16 v[24:27], v[104:107], v[176:179], v[24:27]
	v_mfma_f32_16x16x32_bf16 v[12:15], v[80:83], v[198:201], v[12:15]
	v_mfma_f32_16x16x32_bf16 v[8:11], v[104:107], v[198:201], v[8:11]
	v_mfma_f32_16x16x32_bf16 v[60:63], v[84:87], v[164:167], v[60:63]
	v_mfma_f32_16x16x32_bf16 v[56:59], v[108:111], v[164:167], v[56:59]
	v_mfma_f32_16x16x32_bf16 v[44:47], v[84:87], v[172:175], v[44:47]
	v_mfma_f32_16x16x32_bf16 v[40:43], v[108:111], v[172:175], v[40:43]
	v_mfma_f32_16x16x32_bf16 v[28:31], v[84:87], v[180:183], v[28:31]
	v_mfma_f32_16x16x32_bf16 v[24:27], v[108:111], v[180:183], v[24:27]
	v_mfma_f32_16x16x32_bf16 v[12:15], v[84:87], v[202:205], v[12:15]
	v_mfma_f32_16x16x32_bf16 v[8:11], v[108:111], v[202:205], v[8:11]
	v_mfma_f32_16x16x32_bf16 v[52:55], v[128:131], v[160:163], v[52:55]
	v_mfma_f32_16x16x32_bf16 v[48:51], v[152:155], v[160:163], v[48:51]
	v_mfma_f32_16x16x32_bf16 v[36:39], v[128:131], v[168:171], v[36:39]
	v_mfma_f32_16x16x32_bf16 v[32:35], v[152:155], v[168:171], v[32:35]
	v_mfma_f32_16x16x32_bf16 v[20:23], v[128:131], v[176:179], v[20:23]
	v_mfma_f32_16x16x32_bf16 v[16:19], v[152:155], v[176:179], v[16:19]
	v_mfma_f32_16x16x32_bf16 v[4:7], v[128:131], v[198:201], v[4:7]
	v_mfma_f32_16x16x32_bf16 v[0:3], v[152:155], v[198:201], v[0:3]
	v_mfma_f32_16x16x32_bf16 v[52:55], v[136:139], v[164:167], v[52:55]
	v_mfma_f32_16x16x32_bf16 v[48:51], v[156:159], v[164:167], v[48:51]
	v_mfma_f32_16x16x32_bf16 v[36:39], v[136:139], v[172:175], v[36:39]
	v_mfma_f32_16x16x32_bf16 v[32:35], v[156:159], v[172:175], v[32:35]
	v_mfma_f32_16x16x32_bf16 v[20:23], v[136:139], v[180:183], v[20:23]
	v_mfma_f32_16x16x32_bf16 v[16:19], v[156:159], v[180:183], v[16:19]
	v_mfma_f32_16x16x32_bf16 v[4:7], v[136:139], v[202:205], v[4:7]
	v_mfma_f32_16x16x32_bf16 v[0:3], v[156:159], v[202:205], v[0:3]
	s_barrier
; #define PG8_STAGE(bufoff, gbase, voff) do { _Pragma("unroll") for (int _i = 0; _i < 2; ++_i) \
;         __builtin_amdgcn_global_load_lds((const unsigned*)((const char*)(gbase) + (voff)[_i]), (PG8_LAS unsigned*)(lds + (bufoff) + ldsw + _i * 8192), 16, 0, 0); } while (0)
; #define PG8_LDA(dst, b, h) do { _Pragma("unroll") for (int m = 0; m < 4; ++m) _Pragma("unroll") for (int k = 0; k < 2; ++k) dst[m][k] = *(const PG8_LAS bf16x8*)(lds + PG8_SA(b, h) + aoff + m * 2048 + k * 1024); } while (0)
; #define PG8_LDB(dst, b, h) do { _Pragma("unroll") for (int n = 0; n < 2; ++n) _Pragma("unroll") for (int k = 0; k < 2; ++k) dst[n][k] = *(const PG8_LAS bf16x8*)(lds + PG8_SB(b, h) + boff + n * 2048 + k * 1024); } while (0)
; #define PG8_MMA(ai, bj, At, Bt) do { __builtin_amdgcn_s_setprio(1); _Pragma("unroll") for (int m = 0; m < 4; ++m) _Pragma("unroll") for (int n = 0; n < 2; ++n) _Pragma("unroll") for (int k = 0; k < 2; ++k) \
;         acc[ai][bj][m][n] = __builtin_amdgcn_mfma_f32_16x16x32_bf16(Bt[n][k], At[m][k], acc[ai][bj][m][n], 0, 0, 0); __builtin_amdgcn_s_setprio(0); } while (0)
; #define PG8_WAIT_V(n) asm volatile("s_waitcnt vmcnt(" #n ")" ::: "memory")
; #define PG8_WAIT_L(n) asm volatile("s_waitcnt lgkmcnt(" #n ")" ::: "memory")
; #define PG8_BAR __builtin_amdgcn_s_barrier()
; #define PG8_SCHED __builtin_amdgcn_sched_barrier(0)
; template <class Epi, class Sched, bool ALIGN_EPI = false, bool SP2 = false>
; __device__ __forceinline__ void gemm_phase(PG8_LAS unsigned char* lds, const Gemm g, const Sched& S, const Epi& E) {
;     ...
;             PG8_LDB(B0, 1, 0); PG8_LDB(B1, 1, 1); PG8_SCHED; PG8_LDA(At, 1, 0); PG8_STAGE(PG8_SA(0, 1), a2 + hstep, voffA);
;             PG8_WAIT_V(8); PG8_WAIT_L(0); PG8_BAR; PG8_MMA(0, 0, At, B0); PG8_MMA(0, 1, At, B1); PG8_BAR; PG8_SCHED;
;             PG8_LDA(At, 1, 1); PG8_STAGE(PG8_SB(1, 0), b3, voffB); PG8_STAGE(PG8_SB(1, 1), b3 + hstep, voffB); PG8_STAGE(PG8_SA(1, 0), a3, voffA);
;             PG8_WAIT_V(8); PG8_WAIT_L(0); PG8_BAR; PG8_MMA(1, 0, At, B0); PG8_MMA(1, 1, At, B1); PG8_BAR; PG8_SCHED;
;     ...
;         if constexpr (ALIGN_EPI) { if (wr == 0) PG8_BAR; }
	ds_read_b128 v[80:83], v246 offset:32768
	ds_read_b128 v[84:87], v246 offset:33792
	ds_read_b128 v[104:107], v246 offset:34816
	ds_read_b128 v[108:111], v246 offset:35840
	ds_read_b128 v[128:131], v246 offset:49152
	ds_read_b128 v[136:139], v246 offset:50176
	ds_read_b128 v[152:155], v246 offset:51200
	ds_read_b128 v[156:159], v246 offset:52224
	s_add_u32 s64, s64, 0x4000
	s_addc_u32 s65, s65, 0
	s_mov_b32 m0, s50
	ds_read_b128 v[160:163], v207 offset:32768
	ds_read_b128 v[164:167], v207 offset:33792
	ds_read_b128 v[168:171], v207 offset:34816
	ds_read_b128 v[172:175], v207 offset:35840
	ds_read_b128 v[176:179], v207 offset:36864
	ds_read_b128 v[180:183], v207 offset:37888
	ds_read_b128 v[198:201], v207 offset:38912
	ds_read_b128 v[202:205], v207 offset:39936
	global_load_lds_dwordx4 v184, s[64:65]
	s_mov_b32 m0, s51
	s_nop 0
	global_load_lds_dwordx4 v188, s[64:65]
	s_waitcnt vmcnt(8) lgkmcnt(0)
	s_barrier
	v_mfma_f32_16x16x32_bf16 v[148:151], v[80:83], v[160:163], v[148:151]
	v_mfma_f32_16x16x32_bf16 v[144:147], v[104:107], v[160:163], v[144:147]
	v_mfma_f32_16x16x32_bf16 v[124:127], v[80:83], v[168:171], v[124:127]
	v_mfma_f32_16x16x32_bf16 v[120:123], v[104:107], v[168:171], v[120:123]
	v_mfma_f32_16x16x32_bf16 v[100:103], v[80:83], v[176:179], v[100:103]
	v_mfma_f32_16x16x32_bf16 v[96:99], v[104:107], v[176:179], v[96:99]
	v_mfma_f32_16x16x32_bf16 v[76:79], v[80:83], v[198:201], v[76:79]
	v_mfma_f32_16x16x32_bf16 v[72:75], v[104:107], v[198:201], v[72:75]
	v_mfma_f32_16x16x32_bf16 v[148:151], v[84:87], v[164:167], v[148:151]
	v_mfma_f32_16x16x32_bf16 v[144:147], v[108:111], v[164:167], v[144:147]
	v_mfma_f32_16x16x32_bf16 v[124:127], v[84:87], v[172:175], v[124:127]
	v_mfma_f32_16x16x32_bf16 v[120:123], v[108:111], v[172:175], v[120:123]
	v_mfma_f32_16x16x32_bf16 v[100:103], v[84:87], v[180:183], v[100:103]
	v_mfma_f32_16x16x32_bf16 v[96:99], v[108:111], v[180:183], v[96:99]
	v_mfma_f32_16x16x32_bf16 v[76:79], v[84:87], v[202:205], v[76:79]
	v_mfma_f32_16x16x32_bf16 v[72:75], v[108:111], v[202:205], v[72:75]
	v_mfma_f32_16x16x32_bf16 v[140:143], v[128:131], v[160:163], v[140:143]
	v_mfma_f32_16x16x32_bf16 v[132:135], v[152:155], v[160:163], v[132:135]
	v_mfma_f32_16x16x32_bf16 v[116:119], v[128:131], v[168:171], v[116:119]
	v_mfma_f32_16x16x32_bf16 v[112:115], v[152:155], v[168:171], v[112:115]
	v_mfma_f32_16x16x32_bf16 v[92:95], v[128:131], v[176:179], v[92:95]
	v_mfma_f32_16x16x32_bf16 v[88:91], v[152:155], v[176:179], v[88:91]
	v_mfma_f32_16x16x32_bf16 v[68:71], v[128:131], v[198:201], v[68:71]
	v_mfma_f32_16x16x32_bf16 v[64:67], v[152:155], v[198:201], v[64:67]
	v_mfma_f32_16x16x32_bf16 v[140:143], v[136:139], v[164:167], v[140:143]
	v_mfma_f32_16x16x32_bf16 v[132:135], v[156:159], v[164:167], v[132:135]
	v_mfma_f32_16x16x32_bf16 v[116:119], v[136:139], v[172:175], v[116:119]
	v_mfma_f32_16x16x32_bf16 v[112:115], v[156:159], v[172:175], v[112:115]
	v_mfma_f32_16x16x32_bf16 v[92:95], v[136:139], v[180:183], v[92:95]
	v_mfma_f32_16x16x32_bf16 v[88:91], v[156:159], v[180:183], v[88:91]
	v_mfma_f32_16x16x32_bf16 v[68:71], v[136:139], v[202:205], v[68:71]
	v_mfma_f32_16x16x32_bf16 v[64:67], v[156:159], v[202:205], v[64:67]
	s_barrier
	s_add_u32 s64, s20, 0x8000
	s_addc_u32 s65, s21, 0
	s_add_i32 m0, s39, 0x18000
	ds_read_b128 v[160:163], v207 offset:49152
	ds_read_b128 v[164:167], v207 offset:50176
	ds_read_b128 v[168:171], v207 offset:51200
	ds_read_b128 v[172:175], v207 offset:52224
	ds_read_b128 v[176:179], v207 offset:53248
	ds_read_b128 v[180:183], v207 offset:54272
	ds_read_b128 v[198:201], v207 offset:55296
	ds_read_b128 v[202:205], v207 offset:56320
	global_load_lds_dwordx4 v186, s[64:65]
	s_add_i32 m0, s39, 0x1a000
	s_add_u32 s20, s20, 0xc000
	s_addc_u32 s21, s21, 0
	global_load_lds_dwordx4 v190, s[64:65]
	s_add_i32 m0, s39, 0x1c000
	s_nop 0
	global_load_lds_dwordx4 v186, s[20:21]
	s_add_i32 m0, s39, 0x1e000
	s_nop 0
	global_load_lds_dwordx4 v190, s[20:21]
	s_mov_b32 m0, s56
	s_nop 0
	global_load_lds_dwordx4 v184, s[18:19]
	s_mov_b32 m0, s57
	s_nop 0
	global_load_lds_dwordx4 v188, s[18:19]
	s_waitcnt vmcnt(8) lgkmcnt(0)
	s_barrier
	v_mfma_f32_16x16x32_bf16 v[60:63], v[80:83], v[160:163], v[60:63]
	v_mfma_f32_16x16x32_bf16 v[56:59], v[104:107], v[160:163], v[56:59]
	v_mfma_f32_16x16x32_bf16 v[44:47], v[80:83], v[168:171], v[44:47]
	v_mfma_f32_16x16x32_bf16 v[40:43], v[104:107], v[168:171], v[40:43]
	v_mfma_f32_16x16x32_bf16 v[28:31], v[80:83], v[176:179], v[28:31]
	v_mfma_f32_16x16x32_bf16 v[24:27], v[104:107], v[176:179], v[24:27]
	v_mfma_f32_16x16x32_bf16 v[12:15], v[80:83], v[198:201], v[12:15]
	v_mfma_f32_16x16x32_bf16 v[8:11], v[104:107], v[198:201], v[8:11]
	v_mfma_f32_16x16x32_bf16 v[60:63], v[84:87], v[164:167], v[60:63]
	v_mfma_f32_16x16x32_bf16 v[56:59], v[108:111], v[164:167], v[56:59]
	v_mfma_f32_16x16x32_bf16 v[44:47], v[84:87], v[172:175], v[44:47]
	v_mfma_f32_16x16x32_bf16 v[40:43], v[108:111], v[172:175], v[40:43]
	v_mfma_f32_16x16x32_bf16 v[28:31], v[84:87], v[180:183], v[28:31]
	v_mfma_f32_16x16x32_bf16 v[24:27], v[108:111], v[180:183], v[24:27]
	v_mfma_f32_16x16x32_bf16 v[12:15], v[84:87], v[202:205], v[12:15]
	v_mfma_f32_16x16x32_bf16 v[8:11], v[108:111], v[202:205], v[8:11]
	v_mfma_f32_16x16x32_bf16 v[52:55], v[128:131], v[160:163], v[52:55]
	v_mfma_f32_16x16x32_bf16 v[48:51], v[152:155], v[160:163], v[48:51]
	v_mfma_f32_16x16x32_bf16 v[36:39], v[128:131], v[168:171], v[36:39]
	v_mfma_f32_16x16x32_bf16 v[32:35], v[152:155], v[168:171], v[32:35]
	v_mfma_f32_16x16x32_bf16 v[20:23], v[128:131], v[176:179], v[20:23]
	v_mfma_f32_16x16x32_bf16 v[16:19], v[152:155], v[176:179], v[16:19]
	v_mfma_f32_16x16x32_bf16 v[4:7], v[128:131], v[198:201], v[4:7]
	v_mfma_f32_16x16x32_bf16 v[0:3], v[152:155], v[198:201], v[0:3]
	v_mfma_f32_16x16x32_bf16 v[52:55], v[136:139], v[164:167], v[52:55]
	v_mfma_f32_16x16x32_bf16 v[48:51], v[156:159], v[164:167], v[48:51]
	v_mfma_f32_16x16x32_bf16 v[36:39], v[136:139], v[172:175], v[36:39]
	v_mfma_f32_16x16x32_bf16 v[32:35], v[156:159], v[172:175], v[32:35]
	v_mfma_f32_16x16x32_bf16 v[20:23], v[136:139], v[180:183], v[20:23]
	v_mfma_f32_16x16x32_bf16 v[16:19], v[156:159], v[180:183], v[16:19]
	v_mfma_f32_16x16x32_bf16 v[4:7], v[136:139], v[202:205], v[4:7]
	v_mfma_f32_16x16x32_bf16 v[0:3], v[156:159], v[202:205], v[0:3]
	s_barrier
	s_cmp_ge_u32 s75, s53
	s_mov_b32 s18, s75
	s_cbranch_scc0 .LBB0_1322
	s_and_b64 vcc, exec, s[12:13]
	s_cbranch_vccz .LBB0_1325
	s_barrier

; #define PG8_STAGE(bufoff, gbase, voff) do { _Pragma("unroll") for (int _i = 0; _i < 2; ++_i) \
;         __builtin_amdgcn_global_load_lds((const unsigned*)((const char*)(gbase) + (voff)[_i]), (PG8_LAS unsigned*)(lds + (bufoff) + ldsw + _i * 8192), 16, 0, 0); } while (0)
; #define PG8_LDA(dst, b, h) do { _Pragma("unroll") for (int m = 0; m < 4; ++m) _Pragma("unroll") for (int k = 0; k < 2; ++k) dst[m][k] = *(const PG8_LAS bf16x8*)(lds + PG8_SA(b, h) + aoff + m * 2048 + k * 1024); } while (0)
; #define PG8_LDB(dst, b, h) do { _Pragma("unroll") for (int n = 0; n < 2; ++n) _Pragma("unroll") for (int k = 0; k < 2; ++k) dst[n][k] = *(const PG8_LAS bf16x8*)(lds + PG8_SB(b, h) + boff + n * 2048 + k * 1024); } while (0)
; #define PG8_WAIT_V(n) asm volatile("s_waitcnt vmcnt(" #n ")" ::: "memory")
; #define PG8_WAIT_L(n) asm volatile("s_waitcnt lgkmcnt(" #n ")" ::: "memory")
; #define PG8_BAR __builtin_amdgcn_s_barrier()
; #define PG8_SCHED __builtin_amdgcn_sched_barrier(0)
; template <class Epi, class Sched, bool ALIGN_EPI = false, bool SP2 = false>
; __device__ __forceinline__ void gemm_phase(PG8_LAS unsigned char* lds, const Gemm g, const Sched& S, const Epi& E) {
;     ...
;         const bool has_next = S.next(ui + 1, nxt);
;         const char* nA = has_next ? (const char*)g.A + (size_t)nxt.pm * tstep : cA; const char* nB = has_next ? (const char*)g.Bt + (size_t)nxt.pn * tstep : cB;
;         for (int t = 0; t < nt; t += 2) {
;             const bool last = (t == nt - 2);
;             const char* a1 = cA + (size_t)(t + 1) * kstep;
;             const char* a2 = last ? nA : cA + (size_t)(t + 2) * kstep; const char* b2 = last ? nB : cB + (size_t)(t + 2) * kstep;
;             const char* a3 = a2 + kstep; const char* b3 = b2 + kstep;
;             if (last && has_next) S.a_ready(nxt);
;             if constexpr (SP2) {
;             PG8_LDB(B0, 0, 0); PG8_LDB(B1, 0, 1); PG8_SCHED; PG8_LDA(At, 0, 0); PG8_STAGE(PG8_SA(1, 1), a1 + hstep, voffA);
;             PG8_WAIT_V(8); PG8_WAIT_L(0); PG8_BAR; PG8_MMA(0, 0, At, B0); PG8_MMA(0, 1, At, B1); PG8_BAR; PG8_SCHED;
;             PG8_LDA(At, 0, 1); PG8_STAGE(PG8_SB(0, 0), b2, voffB); PG8_STAGE(PG8_SB(0, 1), b2 + hstep, voffB); PG8_STAGE(PG8_SA(0, 0), a2, voffA);
;             PG8_WAIT_V(8); PG8_WAIT_L(0); PG8_BAR; PG8_MMA(1, 0, At, B0); PG8_MMA(1, 1, At, B1); PG8_BAR; PG8_SCHED;
.LBB0_1355:
	s_ashr_i32 s11, s10, 31
	s_lshl_b64 s[12:13], s[10:11], 19
	s_add_u32 s12, s22, s12
	s_addc_u32 s13, s23, s13
	s_and_b64 s[14:15], s[2:3], exec
	s_cselect_b32 s11, s13, s19
	s_cselect_b32 s40, s12, s18
	s_ashr_i32 s9, s8, 31
	s_lshl_b64 s[14:15], s[8:9], 19
	s_add_u32 s14, s27, s14
	s_addc_u32 s15, s28, s15
	s_and_b64 s[62:63], s[2:3], exec
	s_cselect_b32 s9, s15, s21
	s_cselect_b32 s61, s14, s20
	s_add_u32 s18, s18, 0xc000
	s_addc_u32 s19, s19, 0
	s_add_u32 s66, s20, 0x10000
	v_mov_b32_e32 v0, 0
	s_addc_u32 s67, s21, 0
	s_mov_b32 s68, -2
	v_add_u32_e32 v246, 0x10000, v162
	s_add_u32 s20, s18, 0x4000
	s_addc_u32 s21, s19, 0
	s_cmp_eq_u32 s68, 12
	s_cselect_b32 s64, s40, s20
	s_cselect_b32 s65, s11, s21
	s_cselect_b32 s62, s61, s66
	s_cselect_b32 s63, s9, s67
	ds_read_b128 v[128:131], v246
	ds_read_b128 v[132:135], v246 offset:1024
	ds_read_b128 v[136:139], v246 offset:2048
	ds_read_b128 v[140:143], v246 offset:3072
	ds_read_b128 v[156:159], v246 offset:16384
	ds_read_b128 v[164:167], v246 offset:17408
	ds_read_b128 v[168:171], v246 offset:18432
	ds_read_b128 v[172:175], v246 offset:19456
	s_add_i32 m0, s37, 0xc000
	ds_read_b128 v[176:179], v163
	ds_read_b128 v[180:183], v163 offset:1024
	ds_read_b128 v[184:187], v163 offset:2048
	ds_read_b128 v[188:191], v163 offset:3072
	ds_read_b128 v[192:195], v163 offset:4096
	ds_read_b128 v[196:199], v163 offset:5120
	ds_read_b128 v[200:203], v163 offset:6144
	ds_read_b128 v[204:207], v163 offset:7168
	global_load_lds_dwordx4 v152, s[18:19]
	s_add_i32 m0, s37, 0xe000
	s_add_u32 s20, s64, 0x8000
	s_addc_u32 s21, s65, 0
	global_load_lds_dwordx4 v154, s[18:19]
	s_waitcnt vmcnt(8) lgkmcnt(0)
	s_barrier
	v_mfma_f32_16x16x32_bf16 v[124:127], v[128:131], v[176:179], 0
	v_mfma_f32_16x16x32_bf16 v[120:123], v[136:139], v[176:179], 0
	v_mfma_f32_16x16x32_bf16 v[108:111], v[128:131], v[184:187], 0
	v_mfma_f32_16x16x32_bf16 v[104:107], v[136:139], v[184:187], 0
	v_mfma_f32_16x16x32_bf16 v[92:95], v[128:131], v[192:195], 0
	v_mfma_f32_16x16x32_bf16 v[88:91], v[136:139], v[192:195], 0
	v_mfma_f32_16x16x32_bf16 v[76:79], v[128:131], v[200:203], 0
	v_mfma_f32_16x16x32_bf16 v[72:75], v[136:139], v[200:203], 0
	v_mfma_f32_16x16x32_bf16 v[124:127], v[132:135], v[180:183], v[124:127]
	v_mfma_f32_16x16x32_bf16 v[120:123], v[140:143], v[180:183], v[120:123]
	v_mfma_f32_16x16x32_bf16 v[108:111], v[132:135], v[188:191], v[108:111]
	v_mfma_f32_16x16x32_bf16 v[104:107], v[140:143], v[188:191], v[104:107]
	v_mfma_f32_16x16x32_bf16 v[92:95], v[132:135], v[196:199], v[92:95]
	v_mfma_f32_16x16x32_bf16 v[88:91], v[140:143], v[196:199], v[88:91]
	v_mfma_f32_16x16x32_bf16 v[76:79], v[132:135], v[204:207], v[76:79]
	v_mfma_f32_16x16x32_bf16 v[72:75], v[140:143], v[204:207], v[72:75]
	v_mfma_f32_16x16x32_bf16 v[116:119], v[156:159], v[176:179], 0
	v_mfma_f32_16x16x32_bf16 v[112:115], v[168:171], v[176:179], 0
	v_mfma_f32_16x16x32_bf16 v[100:103], v[156:159], v[184:187], 0
	v_mfma_f32_16x16x32_bf16 v[96:99], v[168:171], v[184:187], 0
	v_mfma_f32_16x16x32_bf16 v[84:87], v[156:159], v[192:195], 0
	v_mfma_f32_16x16x32_bf16 v[80:83], v[168:171], v[192:195], 0
	v_mfma_f32_16x16x32_bf16 v[68:71], v[156:159], v[200:203], 0
	v_mfma_f32_16x16x32_bf16 v[64:67], v[168:171], v[200:203], 0
	v_mfma_f32_16x16x32_bf16 v[116:119], v[164:167], v[180:183], v[116:119]
	v_mfma_f32_16x16x32_bf16 v[112:115], v[172:175], v[180:183], v[112:115]
	v_mfma_f32_16x16x32_bf16 v[100:103], v[164:167], v[188:191], v[100:103]
	v_mfma_f32_16x16x32_bf16 v[96:99], v[172:175], v[188:191], v[96:99]
	v_mfma_f32_16x16x32_bf16 v[84:87], v[164:167], v[196:199], v[84:87]
	v_mfma_f32_16x16x32_bf16 v[80:83], v[172:175], v[196:199], v[80:83]
	v_mfma_f32_16x16x32_bf16 v[68:71], v[164:167], v[204:207], v[68:71]
	v_mfma_f32_16x16x32_bf16 v[64:67], v[172:175], v[204:207], v[64:67]
	s_barrier
	s_add_i32 m0, s30, 0x10000
	ds_read_b128 v[176:179], v163 offset:16384
	ds_read_b128 v[180:183], v163 offset:17408
	ds_read_b128 v[184:187], v163 offset:18432
	ds_read_b128 v[188:191], v163 offset:19456
	ds_read_b128 v[192:195], v163 offset:20480
	ds_read_b128 v[196:199], v163 offset:21504
	ds_read_b128 v[200:203], v163 offset:22528
	ds_read_b128 v[204:207], v163 offset:23552
	global_load_lds_dwordx4 v148, s[62:63]
	s_add_i32 m0, s30, 0x12000
	s_add_u32 s70, s62, 0x4000
	s_addc_u32 s71, s63, 0
	global_load_lds_dwordx4 v144, s[62:63]
	s_add_i32 m0, s30, 0x14000
	s_add_u32 s18, s18, 0x10000
	s_addc_u32 s19, s19, 0
	global_load_lds_dwordx4 v148, s[70:71]
	s_add_i32 m0, s30, 0x16000
	s_add_u32 s66, s66, 0x10000
	s_addc_u32 s67, s67, 0
	global_load_lds_dwordx4 v144, s[70:71]
	s_mov_b32 m0, s37
	s_nop 0
	global_load_lds_dwordx4 v150, s[64:65]
	s_mov_b32 m0, s39
	s_nop 0
	global_load_lds_dwordx4 v146, s[64:65]
	s_waitcnt vmcnt(8) lgkmcnt(0)
	s_barrier
; #define PG8_STAGE(bufoff, gbase, voff) do { _Pragma("unroll") for (int _i = 0; _i < 2; ++_i) \
;         __builtin_amdgcn_global_load_lds((const unsigned*)((const char*)(gbase) + (voff)[_i]), (PG8_LAS unsigned*)(lds + (bufoff) + ldsw + _i * 8192), 16, 0, 0); } while (0)
; #define PG8_LDA(dst, b, h) do { _Pragma("unroll") for (int m = 0; m < 4; ++m) _Pragma("unroll") for (int k = 0; k < 2; ++k) dst[m][k] = *(const PG8_LAS bf16x8*)(lds + PG8_SA(b, h) + aoff + m * 2048 + k * 1024); } while (0)
; #define PG8_LDB(dst, b, h) do { _Pragma("unroll") for (int n = 0; n < 2; ++n) _Pragma("unroll") for (int k = 0; k < 2; ++k) dst[n][k] = *(const PG8_LAS bf16x8*)(lds + PG8_SB(b, h) + boff + n * 2048 + k * 1024); } while (0)
; #define PG8_MMA(ai, bj, At, Bt) do { __builtin_amdgcn_s_setprio(1); _Pragma("unroll") for (int m = 0; m < 4; ++m) _Pragma("unroll") for (int n = 0; n < 2; ++n) _Pragma("unroll") for (int k = 0; k < 2; ++k) \
;         acc[ai][bj][m][n] = __builtin_amdgcn_mfma_f32_16x16x32_bf16(Bt[n][k], At[m][k], acc[ai][bj][m][n], 0, 0, 0); __builtin_amdgcn_s_setprio(0); } while (0)
; #define PG8_WAIT_V(n) asm volatile("s_waitcnt vmcnt(" #n ")" ::: "memory")
; #define PG8_WAIT_L(n) asm volatile("s_waitcnt lgkmcnt(" #n ")" ::: "memory")
; #define PG8_BAR __builtin_amdgcn_s_barrier()
; #define PG8_SCHED __builtin_amdgcn_sched_barrier(0)
; template <class Epi, class Sched, bool ALIGN_EPI = false, bool SP2 = false>
; __device__ __forceinline__ void gemm_phase(PG8_LAS unsigned char* lds, const Gemm g, const Sched& S, const Epi& E) {
;     ...
;             PG8_WAIT_V(8); PG8_WAIT_L(0); PG8_BAR; PG8_MMA(1, 0, At, B0); PG8_MMA(1, 1, At, B1); PG8_BAR; PG8_SCHED;
;             PG8_LDB(B0, 1, 0); PG8_LDB(B1, 1, 1); PG8_SCHED; PG8_LDA(At, 1, 0); PG8_STAGE(PG8_SA(0, 1), a2 + hstep, voffA);
;             PG8_WAIT_V(8); PG8_WAIT_L(0); PG8_BAR; PG8_MMA(0, 0, At, B0); PG8_MMA(0, 1, At, B1); PG8_BAR; PG8_SCHED;
	v_mfma_f32_16x16x32_bf16 v[60:63], v[128:131], v[176:179], 0
	v_mfma_f32_16x16x32_bf16 v[56:59], v[136:139], v[176:179], 0
	v_mfma_f32_16x16x32_bf16 v[44:47], v[128:131], v[184:187], 0
	v_mfma_f32_16x16x32_bf16 v[40:43], v[136:139], v[184:187], 0
	v_mfma_f32_16x16x32_bf16 v[28:31], v[128:131], v[192:195], 0
	v_mfma_f32_16x16x32_bf16 v[24:27], v[136:139], v[192:195], 0
	v_mfma_f32_16x16x32_bf16 v[12:15], v[128:131], v[200:203], 0
	v_mfma_f32_16x16x32_bf16 v[8:11], v[136:139], v[200:203], 0
	v_mfma_f32_16x16x32_bf16 v[60:63], v[132:135], v[180:183], v[60:63]
	v_mfma_f32_16x16x32_bf16 v[56:59], v[140:143], v[180:183], v[56:59]
	v_mfma_f32_16x16x32_bf16 v[44:47], v[132:135], v[188:191], v[44:47]
	v_mfma_f32_16x16x32_bf16 v[40:43], v[140:143], v[188:191], v[40:43]
	v_mfma_f32_16x16x32_bf16 v[28:31], v[132:135], v[196:199], v[28:31]
	v_mfma_f32_16x16x32_bf16 v[24:27], v[140:143], v[196:199], v[24:27]
	v_mfma_f32_16x16x32_bf16 v[12:15], v[132:135], v[204:207], v[12:15]
	v_mfma_f32_16x16x32_bf16 v[8:11], v[140:143], v[204:207], v[8:11]
	v_mfma_f32_16x16x32_bf16 v[52:55], v[156:159], v[176:179], 0
	v_mfma_f32_16x16x32_bf16 v[48:51], v[168:171], v[176:179], 0
	v_mfma_f32_16x16x32_bf16 v[36:39], v[156:159], v[184:187], 0
	v_mfma_f32_16x16x32_bf16 v[32:35], v[168:171], v[184:187], 0
	v_mfma_f32_16x16x32_bf16 v[20:23], v[156:159], v[192:195], 0
	v_mfma_f32_16x16x32_bf16 v[16:19], v[168:171], v[192:195], 0
	v_mfma_f32_16x16x32_bf16 v[4:7], v[156:159], v[200:203], 0
	v_mfma_f32_16x16x32_bf16 v[0:3], v[168:171], v[200:203], 0
	v_mfma_f32_16x16x32_bf16 v[52:55], v[164:167], v[180:183], v[52:55]
	v_mfma_f32_16x16x32_bf16 v[48:51], v[172:175], v[180:183], v[48:51]
	v_mfma_f32_16x16x32_bf16 v[36:39], v[164:167], v[188:191], v[36:39]
	v_mfma_f32_16x16x32_bf16 v[32:35], v[172:175], v[188:191], v[32:35]
	v_mfma_f32_16x16x32_bf16 v[20:23], v[164:167], v[196:199], v[20:23]
	v_mfma_f32_16x16x32_bf16 v[16:19], v[172:175], v[196:199], v[16:19]
	v_mfma_f32_16x16x32_bf16 v[4:7], v[164:167], v[204:207], v[4:7]
	v_mfma_f32_16x16x32_bf16 v[0:3], v[172:175], v[204:207], v[0:3]
	s_barrier
	ds_read_b128 v[128:131], v246 offset:32768
	ds_read_b128 v[132:135], v246 offset:33792
	ds_read_b128 v[136:139], v246 offset:34816
	ds_read_b128 v[140:143], v246 offset:35840
	ds_read_b128 v[156:159], v246 offset:49152
	ds_read_b128 v[164:167], v246 offset:50176
	ds_read_b128 v[168:171], v246 offset:51200
	ds_read_b128 v[172:175], v246 offset:52224
	s_add_u32 s64, s64, 0x4000
	s_addc_u32 s65, s65, 0
	s_mov_b32 m0, s41
	ds_read_b128 v[176:179], v163 offset:32768
	ds_read_b128 v[180:183], v163 offset:33792
	ds_read_b128 v[184:187], v163 offset:34816
	ds_read_b128 v[188:191], v163 offset:35840
	ds_read_b128 v[192:195], v163 offset:36864
	ds_read_b128 v[196:199], v163 offset:37888
	ds_read_b128 v[200:203], v163 offset:38912
	ds_read_b128 v[204:207], v163 offset:39936
	global_load_lds_dwordx4 v150, s[64:65]
	s_mov_b32 m0, s42
	s_nop 0
	global_load_lds_dwordx4 v146, s[64:65]
	s_waitcnt vmcnt(8) lgkmcnt(0)
	s_barrier
	v_mfma_f32_16x16x32_bf16 v[124:127], v[128:131], v[176:179], v[124:127]
	v_mfma_f32_16x16x32_bf16 v[120:123], v[136:139], v[176:179], v[120:123]
	v_mfma_f32_16x16x32_bf16 v[108:111], v[128:131], v[184:187], v[108:111]
	v_mfma_f32_16x16x32_bf16 v[104:107], v[136:139], v[184:187], v[104:107]
	v_mfma_f32_16x16x32_bf16 v[92:95], v[128:131], v[192:195], v[92:95]
	v_mfma_f32_16x16x32_bf16 v[88:91], v[136:139], v[192:195], v[88:91]
	v_mfma_f32_16x16x32_bf16 v[76:79], v[128:131], v[200:203], v[76:79]
	v_mfma_f32_16x16x32_bf16 v[72:75], v[136:139], v[200:203], v[72:75]
	v_mfma_f32_16x16x32_bf16 v[124:127], v[132:135], v[180:183], v[124:127]
	v_mfma_f32_16x16x32_bf16 v[120:123], v[140:143], v[180:183], v[120:123]
	v_mfma_f32_16x16x32_bf16 v[108:111], v[132:135], v[188:191], v[108:111]
	v_mfma_f32_16x16x32_bf16 v[104:107], v[140:143], v[188:191], v[104:107]
	v_mfma_f32_16x16x32_bf16 v[92:95], v[132:135], v[196:199], v[92:95]
	v_mfma_f32_16x16x32_bf16 v[88:91], v[140:143], v[196:199], v[88:91]
	v_mfma_f32_16x16x32_bf16 v[76:79], v[132:135], v[204:207], v[76:79]
	v_mfma_f32_16x16x32_bf16 v[72:75], v[140:143], v[204:207], v[72:75]
	v_mfma_f32_16x16x32_bf16 v[116:119], v[156:159], v[176:179], v[116:119]
	v_mfma_f32_16x16x32_bf16 v[112:115], v[168:171], v[176:179], v[112:115]
	v_mfma_f32_16x16x32_bf16 v[100:103], v[156:159], v[184:187], v[100:103]
	v_mfma_f32_16x16x32_bf16 v[96:99], v[168:171], v[184:187], v[96:99]
	v_mfma_f32_16x16x32_bf16 v[84:87], v[156:159], v[192:195], v[84:87]
	v_mfma_f32_16x16x32_bf16 v[80:83], v[168:171], v[192:195], v[80:83]
	v_mfma_f32_16x16x32_bf16 v[68:71], v[156:159], v[200:203], v[68:71]
	v_mfma_f32_16x16x32_bf16 v[64:67], v[168:171], v[200:203], v[64:67]
	v_mfma_f32_16x16x32_bf16 v[116:119], v[164:167], v[180:183], v[116:119]
	v_mfma_f32_16x16x32_bf16 v[112:115], v[172:175], v[180:183], v[112:115]
	v_mfma_f32_16x16x32_bf16 v[100:103], v[164:167], v[188:191], v[100:103]
	v_mfma_f32_16x16x32_bf16 v[96:99], v[172:175], v[188:191], v[96:99]
	v_mfma_f32_16x16x32_bf16 v[84:87], v[164:167], v[196:199], v[84:87]
	v_mfma_f32_16x16x32_bf16 v[80:83], v[172:175], v[196:199], v[80:83]
	v_mfma_f32_16x16x32_bf16 v[68:71], v[164:167], v[204:207], v[68:71]
	v_mfma_f32_16x16x32_bf16 v[64:67], v[172:175], v[204:207], v[64:67]
	s_barrier
; #define PG8_STAGE(bufoff, gbase, voff) do { _Pragma("unroll") for (int _i = 0; _i < 2; ++_i) \
;         __builtin_amdgcn_global_load_lds((const unsigned*)((const char*)(gbase) + (voff)[_i]), (PG8_LAS unsigned*)(lds + (bufoff) + ldsw + _i * 8192), 16, 0, 0); } while (0)
; #define PG8_LDA(dst, b, h) do { _Pragma("unroll") for (int m = 0; m < 4; ++m) _Pragma("unroll") for (int k = 0; k < 2; ++k) dst[m][k] = *(const PG8_LAS bf16x8*)(lds + PG8_SA(b, h) + aoff + m * 2048 + k * 1024); } while (0)
; #define PG8_LDB(dst, b, h) do { _Pragma("unroll") for (int n = 0; n < 2; ++n) _Pragma("unroll") for (int k = 0; k < 2; ++k) dst[n][k] = *(const PG8_LAS bf16x8*)(lds + PG8_SB(b, h) + boff + n * 2048 + k * 1024); } while (0)
; template <class Epi, class Sched, bool ALIGN_EPI = false, bool SP2 = false>
; __device__ __forceinline__ void gemm_phase(PG8_LAS unsigned char* lds, const Gemm g, const Sched& S, const Epi& E) {
;     ...
;         for (int t = 0; t < nt; t += 2) {
;             const bool last = (t == nt - 2);
;             const char* a1 = cA + (size_t)(t + 1) * kstep;
;             const char* a2 = last ? nA : cA + (size_t)(t + 2) * kstep; const char* b2 = last ? nB : cB + (size_t)(t + 2) * kstep;
;             const char* a3 = a2 + kstep; const char* b3 = b2 + kstep;
;             if (last && has_next) S.a_ready(nxt);
;             if constexpr (SP2) {
;             PG8_LDB(B0, 0, 0); PG8_LDB(B1, 0, 1); PG8_SCHED; PG8_LDA(At, 0, 0); PG8_STAGE(PG8_SA(1, 1), a1 + hstep, voffA);
;             PG8_WAIT_V(8); PG8_WAIT_L(0); PG8_BAR; PG8_MMA(0, 0, At, B0); PG8_MMA(0, 1, At, B1); PG8_BAR; PG8_SCHED;
;             PG8_LDA(At, 0, 1); PG8_STAGE(PG8_SB(0, 0), b2, voffB); PG8_STAGE(PG8_SB(0, 1), b2 + hstep, voffB); PG8_STAGE(PG8_SA(0, 0), a2, voffA);
;             PG8_WAIT_V(8); PG8_WAIT_L(0); PG8_BAR; PG8_MMA(1, 0, At, B0); PG8_MMA(1, 1, At, B1); PG8_BAR; PG8_SCHED;
;             PG8_LDB(B0, 1, 0); PG8_LDB(B1, 1, 1); PG8_SCHED; PG8_LDA(At, 1, 0); PG8_STAGE(PG8_SA(0, 1), a2 + hstep, voffA);
;             PG8_WAIT_V(8); PG8_WAIT_L(0); PG8_BAR; PG8_MMA(0, 0, At, B0); PG8_MMA(0, 1, At, B1); PG8_BAR; PG8_SCHED;
;             PG8_LDA(At, 1, 1); PG8_STAGE(PG8_SB(1, 0), b3, voffB); PG8_STAGE(PG8_SB(1, 1), b3 + hstep, voffB); PG8_STAGE(PG8_SA(1, 0), a3, voffA);
;             PG8_WAIT_V(8); PG8_WAIT_L(0); PG8_BAR; PG8_MMA(1, 0, At, B0); PG8_MMA(1, 1, At, B1); PG8_BAR; PG8_SCHED;
	s_add_u32 s64, s62, 0x8000
	s_addc_u32 s65, s63, 0
	s_add_i32 m0, s30, 0x18000
	ds_read_b128 v[176:179], v163 offset:49152
	ds_read_b128 v[180:183], v163 offset:50176
	ds_read_b128 v[184:187], v163 offset:51200
	ds_read_b128 v[188:191], v163 offset:52224
	ds_read_b128 v[192:195], v163 offset:53248
	ds_read_b128 v[196:199], v163 offset:54272
	ds_read_b128 v[200:203], v163 offset:55296
	ds_read_b128 v[204:207], v163 offset:56320
	global_load_lds_dwordx4 v148, s[64:65]
	s_add_i32 m0, s30, 0x1a000
	s_add_u32 s62, s62, 0xc000
	s_addc_u32 s63, s63, 0
	global_load_lds_dwordx4 v144, s[64:65]
	s_add_i32 m0, s30, 0x1c000
	s_nop 0
	global_load_lds_dwordx4 v148, s[62:63]
	s_add_i32 m0, s30, 0x1e000
	s_nop 0
	global_load_lds_dwordx4 v144, s[62:63]
	s_mov_b32 m0, s54
	s_nop 0
	global_load_lds_dwordx4 v150, s[20:21]
	s_mov_b32 m0, s55
	s_nop 0
	global_load_lds_dwordx4 v146, s[20:21]
	s_waitcnt vmcnt(8) lgkmcnt(0)
	s_barrier
	v_mfma_f32_16x16x32_bf16 v[60:63], v[128:131], v[176:179], v[60:63]
	v_mfma_f32_16x16x32_bf16 v[56:59], v[136:139], v[176:179], v[56:59]
	v_mfma_f32_16x16x32_bf16 v[44:47], v[128:131], v[184:187], v[44:47]
	v_mfma_f32_16x16x32_bf16 v[40:43], v[136:139], v[184:187], v[40:43]
	v_mfma_f32_16x16x32_bf16 v[28:31], v[128:131], v[192:195], v[28:31]
	v_mfma_f32_16x16x32_bf16 v[24:27], v[136:139], v[192:195], v[24:27]
	v_mfma_f32_16x16x32_bf16 v[12:15], v[128:131], v[200:203], v[12:15]
	v_mfma_f32_16x16x32_bf16 v[8:11], v[136:139], v[200:203], v[8:11]
	v_mfma_f32_16x16x32_bf16 v[60:63], v[132:135], v[180:183], v[60:63]
	v_mfma_f32_16x16x32_bf16 v[56:59], v[140:143], v[180:183], v[56:59]
	v_mfma_f32_16x16x32_bf16 v[44:47], v[132:135], v[188:191], v[44:47]
	v_mfma_f32_16x16x32_bf16 v[40:43], v[140:143], v[188:191], v[40:43]
	v_mfma_f32_16x16x32_bf16 v[28:31], v[132:135], v[196:199], v[28:31]
	v_mfma_f32_16x16x32_bf16 v[24:27], v[140:143], v[196:199], v[24:27]
	v_mfma_f32_16x16x32_bf16 v[12:15], v[132:135], v[204:207], v[12:15]
	v_mfma_f32_16x16x32_bf16 v[8:11], v[140:143], v[204:207], v[8:11]
	v_mfma_f32_16x16x32_bf16 v[52:55], v[156:159], v[176:179], v[52:55]
	v_mfma_f32_16x16x32_bf16 v[48:51], v[168:171], v[176:179], v[48:51]
	v_mfma_f32_16x16x32_bf16 v[36:39], v[156:159], v[184:187], v[36:39]
	v_mfma_f32_16x16x32_bf16 v[32:35], v[168:171], v[184:187], v[32:35]
	v_mfma_f32_16x16x32_bf16 v[20:23], v[156:159], v[192:195], v[20:23]
	v_mfma_f32_16x16x32_bf16 v[16:19], v[168:171], v[192:195], v[16:19]
	v_mfma_f32_16x16x32_bf16 v[4:7], v[156:159], v[200:203], v[4:7]
	v_mfma_f32_16x16x32_bf16 v[0:3], v[168:171], v[200:203], v[0:3]
	v_mfma_f32_16x16x32_bf16 v[52:55], v[164:167], v[180:183], v[52:55]
	v_mfma_f32_16x16x32_bf16 v[48:51], v[172:175], v[180:183], v[48:51]
	v_mfma_f32_16x16x32_bf16 v[36:39], v[164:167], v[188:191], v[36:39]
	v_mfma_f32_16x16x32_bf16 v[32:35], v[172:175], v[188:191], v[32:35]
	v_mfma_f32_16x16x32_bf16 v[20:23], v[164:167], v[196:199], v[20:23]
	v_mfma_f32_16x16x32_bf16 v[16:19], v[172:175], v[196:199], v[16:19]
	v_mfma_f32_16x16x32_bf16 v[4:7], v[164:167], v[204:207], v[4:7]
	v_mfma_f32_16x16x32_bf16 v[0:3], v[172:175], v[204:207], v[0:3]
	s_barrier
	s_add_i32 s68, s68, 2
	s_cmp_gt_u32 s68, 13
.LBB0_1356:
	s_add_u32 s20, s18, 0x4000
	s_addc_u32 s21, s19, 0
	s_cmp_eq_u32 s68, 12
	s_cselect_b32 s64, s40, s20
	s_cselect_b32 s65, s11, s21
	s_cselect_b32 s62, s61, s66
	s_cselect_b32 s63, s9, s67
	ds_read_b128 v[128:131], v246
	ds_read_b128 v[132:135], v246 offset:1024
	ds_read_b128 v[136:139], v246 offset:2048
	ds_read_b128 v[140:143], v246 offset:3072
	ds_read_b128 v[156:159], v246 offset:16384
	ds_read_b128 v[164:167], v246 offset:17408
	ds_read_b128 v[168:171], v246 offset:18432
	ds_read_b128 v[172:175], v246 offset:19456
	s_add_i32 m0, s37, 0xc000
	ds_read_b128 v[176:179], v163
	ds_read_b128 v[180:183], v163 offset:1024
	ds_read_b128 v[184:187], v163 offset:2048
	ds_read_b128 v[188:191], v163 offset:3072
	ds_read_b128 v[192:195], v163 offset:4096
	ds_read_b128 v[196:199], v163 offset:5120
	ds_read_b128 v[200:203], v163 offset:6144
	ds_read_b128 v[204:207], v163 offset:7168
	global_load_lds_dwordx4 v152, s[18:19]
	s_add_i32 m0, s37, 0xe000
	s_add_u32 s20, s64, 0x8000
	s_addc_u32 s21, s65, 0
	global_load_lds_dwordx4 v154, s[18:19]
	s_waitcnt vmcnt(8) lgkmcnt(0)
	s_barrier
	v_mfma_f32_16x16x32_bf16 v[124:127], v[128:131], v[176:179], v[124:127]
	v_mfma_f32_16x16x32_bf16 v[120:123], v[136:139], v[176:179], v[120:123]
	v_mfma_f32_16x16x32_bf16 v[108:111], v[128:131], v[184:187], v[108:111]
	v_mfma_f32_16x16x32_bf16 v[104:107], v[136:139], v[184:187], v[104:107]
	v_mfma_f32_16x16x32_bf16 v[92:95], v[128:131], v[192:195], v[92:95]
	v_mfma_f32_16x16x32_bf16 v[88:91], v[136:139], v[192:195], v[88:91]
	v_mfma_f32_16x16x32_bf16 v[76:79], v[128:131], v[200:203], v[76:79]
	v_mfma_f32_16x16x32_bf16 v[72:75], v[136:139], v[200:203], v[72:75]
	v_mfma_f32_16x16x32_bf16 v[124:127], v[132:135], v[180:183], v[124:127]
	v_mfma_f32_16x16x32_bf16 v[120:123], v[140:143], v[180:183], v[120:123]
	v_mfma_f32_16x16x32_bf16 v[108:111], v[132:135], v[188:191], v[108:111]
	v_mfma_f32_16x16x32_bf16 v[104:107], v[140:143], v[188:191], v[104:107]
	v_mfma_f32_16x16x32_bf16 v[92:95], v[132:135], v[196:199], v[92:95]
	v_mfma_f32_16x16x32_bf16 v[88:91], v[140:143], v[196:199], v[88:91]
	v_mfma_f32_16x16x32_bf16 v[76:79], v[132:135], v[204:207], v[76:79]
	v_mfma_f32_16x16x32_bf16 v[72:75], v[140:143], v[204:207], v[72:75]
	v_mfma_f32_16x16x32_bf16 v[116:119], v[156:159], v[176:179], v[116:119]
	v_mfma_f32_16x16x32_bf16 v[112:115], v[168:171], v[176:179], v[112:115]
	v_mfma_f32_16x16x32_bf16 v[100:103], v[156:159], v[184:187], v[100:103]
	v_mfma_f32_16x16x32_bf16 v[96:99], v[168:171], v[184:187], v[96:99]
	v_mfma_f32_16x16x32_bf16 v[84:87], v[156:159], v[192:195], v[84:87]
	v_mfma_f32_16x16x32_bf16 v[80:83], v[168:171], v[192:195], v[80:83]
	v_mfma_f32_16x16x32_bf16 v[68:71], v[156:159], v[200:203], v[68:71]
	v_mfma_f32_16x16x32_bf16 v[64:67], v[168:171], v[200:203], v[64:67]
	v_mfma_f32_16x16x32_bf16 v[116:119], v[164:167], v[180:183], v[116:119]
	v_mfma_f32_16x16x32_bf16 v[112:115], v[172:175], v[180:183], v[112:115]
	v_mfma_f32_16x16x32_bf16 v[100:103], v[164:167], v[188:191], v[100:103]
	v_mfma_f32_16x16x32_bf16 v[96:99], v[172:175], v[188:191], v[96:99]
	v_mfma_f32_16x16x32_bf16 v[84:87], v[164:167], v[196:199], v[84:87]
	v_mfma_f32_16x16x32_bf16 v[80:83], v[172:175], v[196:199], v[80:83]
	v_mfma_f32_16x16x32_bf16 v[68:71], v[164:167], v[204:207], v[68:71]
	v_mfma_f32_16x16x32_bf16 v[64:67], v[172:175], v[204:207], v[64:67]
	s_barrier
; #define PG8_STAGE(bufoff, gbase, voff) do { _Pragma("unroll") for (int _i = 0; _i < 2; ++_i) \
;         __builtin_amdgcn_global_load_lds((const unsigned*)((const char*)(gbase) + (voff)[_i]), (PG8_LAS unsigned*)(lds + (bufoff) + ldsw + _i * 8192), 16, 0, 0); } while (0)
; #define PG8_LDA(dst, b, h) do { _Pragma("unroll") for (int m = 0; m < 4; ++m) _Pragma("unroll") for (int k = 0; k < 2; ++k) dst[m][k] = *(const PG8_LAS bf16x8*)(lds + PG8_SA(b, h) + aoff + m * 2048 + k * 1024); } while (0)
; #define PG8_LDB(dst, b, h) do { _Pragma("unroll") for (int n = 0; n < 2; ++n) _Pragma("unroll") for (int k = 0; k < 2; ++k) dst[n][k] = *(const PG8_LAS bf16x8*)(lds + PG8_SB(b, h) + boff + n * 2048 + k * 1024); } while (0)
; #define PG8_MMA(ai, bj, At, Bt) do { __builtin_amdgcn_s_setprio(1); _Pragma("unroll") for (int m = 0; m < 4; ++m) _Pragma("unroll") for (int n = 0; n < 2; ++n) _Pragma("unroll") for (int k = 0; k < 2; ++k) \
;         acc[ai][bj][m][n] = __builtin_amdgcn_mfma_f32_16x16x32_bf16(Bt[n][k], At[m][k], acc[ai][bj][m][n], 0, 0, 0); __builtin_amdgcn_s_setprio(0); } while (0)
; #define PG8_WAIT_V(n) asm volatile("s_waitcnt vmcnt(" #n ")" ::: "memory")
; #define PG8_WAIT_L(n) asm volatile("s_waitcnt lgkmcnt(" #n ")" ::: "memory")
; #define PG8_BAR __builtin_amdgcn_s_barrier()
; #define PG8_SCHED __builtin_amdgcn_sched_barrier(0)
; template <class Epi, class Sched, bool ALIGN_EPI = false, bool SP2 = false>
; __device__ __forceinline__ void gemm_phase(PG8_LAS unsigned char* lds, const Gemm g, const Sched& S, const Epi& E) {
;     ...
;             PG8_LDA(At, 0, 1); PG8_STAGE(PG8_SB(0, 0), b2, voffB); PG8_STAGE(PG8_SB(0, 1), b2 + hstep, voffB); PG8_STAGE(PG8_SA(0, 0), a2, voffA);
;             PG8_WAIT_V(8); PG8_WAIT_L(0); PG8_BAR; PG8_MMA(1, 0, At, B0); PG8_MMA(1, 1, At, B1); PG8_BAR; PG8_SCHED;
;             PG8_LDB(B0, 1, 0); PG8_LDB(B1, 1, 1); PG8_SCHED; PG8_LDA(At, 1, 0); PG8_STAGE(PG8_SA(0, 1), a2 + hstep, voffA);
	s_add_i32 m0, s30, 0x10000
	ds_read_b128 v[176:179], v163 offset:16384
	ds_read_b128 v[180:183], v163 offset:17408
	ds_read_b128 v[184:187], v163 offset:18432
	ds_read_b128 v[188:191], v163 offset:19456
	ds_read_b128 v[192:195], v163 offset:20480
	ds_read_b128 v[196:199], v163 offset:21504
	ds_read_b128 v[200:203], v163 offset:22528
	ds_read_b128 v[204:207], v163 offset:23552
	global_load_lds_dwordx4 v148, s[62:63]
	s_add_i32 m0, s30, 0x12000
	s_add_u32 s70, s62, 0x4000
	s_addc_u32 s71, s63, 0
	global_load_lds_dwordx4 v144, s[62:63]
	s_add_i32 m0, s30, 0x14000
	s_add_u32 s18, s18, 0x10000
	s_addc_u32 s19, s19, 0
	global_load_lds_dwordx4 v148, s[70:71]
	s_add_i32 m0, s30, 0x16000
	s_add_u32 s66, s66, 0x10000
	s_addc_u32 s67, s67, 0
	global_load_lds_dwordx4 v144, s[70:71]
	s_mov_b32 m0, s37
	s_nop 0
	global_load_lds_dwordx4 v150, s[64:65]
	s_mov_b32 m0, s39
	s_nop 0
	global_load_lds_dwordx4 v146, s[64:65]
	s_waitcnt vmcnt(8) lgkmcnt(0)
	s_barrier
	v_mfma_f32_16x16x32_bf16 v[60:63], v[128:131], v[176:179], v[60:63]
	v_mfma_f32_16x16x32_bf16 v[56:59], v[136:139], v[176:179], v[56:59]
	v_mfma_f32_16x16x32_bf16 v[44:47], v[128:131], v[184:187], v[44:47]
	v_mfma_f32_16x16x32_bf16 v[40:43], v[136:139], v[184:187], v[40:43]
	v_mfma_f32_16x16x32_bf16 v[28:31], v[128:131], v[192:195], v[28:31]
	v_mfma_f32_16x16x32_bf16 v[24:27], v[136:139], v[192:195], v[24:27]
	v_mfma_f32_16x16x32_bf16 v[12:15], v[128:131], v[200:203], v[12:15]
	v_mfma_f32_16x16x32_bf16 v[8:11], v[136:139], v[200:203], v[8:11]
	v_mfma_f32_16x16x32_bf16 v[60:63], v[132:135], v[180:183], v[60:63]
	v_mfma_f32_16x16x32_bf16 v[56:59], v[140:143], v[180:183], v[56:59]
	v_mfma_f32_16x16x32_bf16 v[44:47], v[132:135], v[188:191], v[44:47]
	v_mfma_f32_16x16x32_bf16 v[40:43], v[140:143], v[188:191], v[40:43]
	v_mfma_f32_16x16x32_bf16 v[28:31], v[132:135], v[196:199], v[28:31]
	v_mfma_f32_16x16x32_bf16 v[24:27], v[140:143], v[196:199], v[24:27]
	v_mfma_f32_16x16x32_bf16 v[12:15], v[132:135], v[204:207], v[12:15]
	v_mfma_f32_16x16x32_bf16 v[8:11], v[140:143], v[204:207], v[8:11]
	v_mfma_f32_16x16x32_bf16 v[52:55], v[156:159], v[176:179], v[52:55]
	v_mfma_f32_16x16x32_bf16 v[48:51], v[168:171], v[176:179], v[48:51]
	v_mfma_f32_16x16x32_bf16 v[36:39], v[156:159], v[184:187], v[36:39]
	v_mfma_f32_16x16x32_bf16 v[32:35], v[168:171], v[184:187], v[32:35]
	v_mfma_f32_16x16x32_bf16 v[20:23], v[156:159], v[192:195], v[20:23]
	v_mfma_f32_16x16x32_bf16 v[16:19], v[168:171], v[192:195], v[16:19]
	v_mfma_f32_16x16x32_bf16 v[4:7], v[156:159], v[200:203], v[4:7]
	v_mfma_f32_16x16x32_bf16 v[0:3], v[168:171], v[200:203], v[0:3]
	v_mfma_f32_16x16x32_bf16 v[52:55], v[164:167], v[180:183], v[52:55]
	v_mfma_f32_16x16x32_bf16 v[48:51], v[172:175], v[180:183], v[48:51]
	v_mfma_f32_16x16x32_bf16 v[36:39], v[164:167], v[188:191], v[36:39]
	v_mfma_f32_16x16x32_bf16 v[32:35], v[172:175], v[188:191], v[32:35]
	v_mfma_f32_16x16x32_bf16 v[20:23], v[164:167], v[196:199], v[20:23]
	v_mfma_f32_16x16x32_bf16 v[16:19], v[172:175], v[196:199], v[16:19]
	v_mfma_f32_16x16x32_bf16 v[4:7], v[164:167], v[204:207], v[4:7]
	v_mfma_f32_16x16x32_bf16 v[0:3], v[172:175], v[204:207], v[0:3]
	s_barrier
	ds_read_b128 v[128:131], v246 offset:32768
	ds_read_b128 v[132:135], v246 offset:33792
	ds_read_b128 v[136:139], v246 offset:34816
	ds_read_b128 v[140:143], v246 offset:35840
	ds_read_b128 v[156:159], v246 offset:49152
	ds_read_b128 v[164:167], v246 offset:50176
	ds_read_b128 v[168:171], v246 offset:51200
	ds_read_b128 v[172:175], v246 offset:52224
	s_add_u32 s64, s64, 0x4000
	s_addc_u32 s65, s65, 0
	s_mov_b32 m0, s41
	ds_read_b128 v[176:179], v163 offset:32768
	ds_read_b128 v[180:183], v163 offset:33792
	ds_read_b128 v[184:187], v163 offset:34816
	ds_read_b128 v[188:191], v163 offset:35840
	ds_read_b128 v[192:195], v163 offset:36864
	ds_read_b128 v[196:199], v163 offset:37888
	ds_read_b128 v[200:203], v163 offset:38912
	ds_read_b128 v[204:207], v163 offset:39936
	global_load_lds_dwordx4 v150, s[64:65]
	s_mov_b32 m0, s42
	s_nop 0
	global_load_lds_dwordx4 v146, s[64:65]
	s_waitcnt vmcnt(8) lgkmcnt(0)
	s_barrier
; #define PG8_STAGE(bufoff, gbase, voff) do { _Pragma("unroll") for (int _i = 0; _i < 2; ++_i) \
;         __builtin_amdgcn_global_load_lds((const unsigned*)((const char*)(gbase) + (voff)[_i]), (PG8_LAS unsigned*)(lds + (bufoff) + ldsw + _i * 8192), 16, 0, 0); } while (0)
; #define PG8_LDA(dst, b, h) do { _Pragma("unroll") for (int m = 0; m < 4; ++m) _Pragma("unroll") for (int k = 0; k < 2; ++k) dst[m][k] = *(const PG8_LAS bf16x8*)(lds + PG8_SA(b, h) + aoff + m * 2048 + k * 1024); } while (0)
; #define PG8_MMA(ai, bj, At, Bt) do { __builtin_amdgcn_s_setprio(1); _Pragma("unroll") for (int m = 0; m < 4; ++m) _Pragma("unroll") for (int n = 0; n < 2; ++n) _Pragma("unroll") for (int k = 0; k < 2; ++k) \
;         acc[ai][bj][m][n] = __builtin_amdgcn_mfma_f32_16x16x32_bf16(Bt[n][k], At[m][k], acc[ai][bj][m][n], 0, 0, 0); __builtin_amdgcn_s_setprio(0); } while (0)
; #define PG8_WAIT_V(n) asm volatile("s_waitcnt vmcnt(" #n ")" ::: "memory")
; #define PG8_WAIT_L(n) asm volatile("s_waitcnt lgkmcnt(" #n ")" ::: "memory")
; #define PG8_BAR __builtin_amdgcn_s_barrier()
; #define PG8_SCHED __builtin_amdgcn_sched_barrier(0)
; template <class Epi, class Sched, bool ALIGN_EPI = false, bool SP2 = false>
; __device__ __forceinline__ void gemm_phase(PG8_LAS unsigned char* lds, const Gemm g, const Sched& S, const Epi& E) {
;     ...
;             PG8_WAIT_V(8); PG8_WAIT_L(0); PG8_BAR; PG8_MMA(0, 0, At, B0); PG8_MMA(0, 1, At, B1); PG8_BAR; PG8_SCHED;
;             PG8_LDA(At, 1, 1); PG8_STAGE(PG8_SB(1, 0), b3, voffB); PG8_STAGE(PG8_SB(1, 1), b3 + hstep, voffB); PG8_STAGE(PG8_SA(1, 0), a3, voffA);
;             PG8_WAIT_V(8); PG8_WAIT_L(0); PG8_BAR; PG8_MMA(1, 0, At, B0); PG8_MMA(1, 1, At, B1); PG8_BAR; PG8_SCHED;
;     ...
;         if constexpr (ALIGN_EPI) { if (wr == 0) PG8_BAR; }
	v_mfma_f32_16x16x32_bf16 v[124:127], v[128:131], v[176:179], v[124:127]
	v_mfma_f32_16x16x32_bf16 v[120:123], v[136:139], v[176:179], v[120:123]
	v_mfma_f32_16x16x32_bf16 v[108:111], v[128:131], v[184:187], v[108:111]
	v_mfma_f32_16x16x32_bf16 v[104:107], v[136:139], v[184:187], v[104:107]
	v_mfma_f32_16x16x32_bf16 v[92:95], v[128:131], v[192:195], v[92:95]
	v_mfma_f32_16x16x32_bf16 v[88:91], v[136:139], v[192:195], v[88:91]
	v_mfma_f32_16x16x32_bf16 v[76:79], v[128:131], v[200:203], v[76:79]
	v_mfma_f32_16x16x32_bf16 v[72:75], v[136:139], v[200:203], v[72:75]
	v_mfma_f32_16x16x32_bf16 v[124:127], v[132:135], v[180:183], v[124:127]
	v_mfma_f32_16x16x32_bf16 v[120:123], v[140:143], v[180:183], v[120:123]
	v_mfma_f32_16x16x32_bf16 v[108:111], v[132:135], v[188:191], v[108:111]
	v_mfma_f32_16x16x32_bf16 v[104:107], v[140:143], v[188:191], v[104:107]
	v_mfma_f32_16x16x32_bf16 v[92:95], v[132:135], v[196:199], v[92:95]
	v_mfma_f32_16x16x32_bf16 v[88:91], v[140:143], v[196:199], v[88:91]
	v_mfma_f32_16x16x32_bf16 v[76:79], v[132:135], v[204:207], v[76:79]
	v_mfma_f32_16x16x32_bf16 v[72:75], v[140:143], v[204:207], v[72:75]
	v_mfma_f32_16x16x32_bf16 v[116:119], v[156:159], v[176:179], v[116:119]
	v_mfma_f32_16x16x32_bf16 v[112:115], v[168:171], v[176:179], v[112:115]
	v_mfma_f32_16x16x32_bf16 v[100:103], v[156:159], v[184:187], v[100:103]
	v_mfma_f32_16x16x32_bf16 v[96:99], v[168:171], v[184:187], v[96:99]
	v_mfma_f32_16x16x32_bf16 v[84:87], v[156:159], v[192:195], v[84:87]
	v_mfma_f32_16x16x32_bf16 v[80:83], v[168:171], v[192:195], v[80:83]
	v_mfma_f32_16x16x32_bf16 v[68:71], v[156:159], v[200:203], v[68:71]
	v_mfma_f32_16x16x32_bf16 v[64:67], v[168:171], v[200:203], v[64:67]
	v_mfma_f32_16x16x32_bf16 v[116:119], v[164:167], v[180:183], v[116:119]
	v_mfma_f32_16x16x32_bf16 v[112:115], v[172:175], v[180:183], v[112:115]
	v_mfma_f32_16x16x32_bf16 v[100:103], v[164:167], v[188:191], v[100:103]
	v_mfma_f32_16x16x32_bf16 v[96:99], v[172:175], v[188:191], v[96:99]
	v_mfma_f32_16x16x32_bf16 v[84:87], v[164:167], v[196:199], v[84:87]
	v_mfma_f32_16x16x32_bf16 v[80:83], v[172:175], v[196:199], v[80:83]
	v_mfma_f32_16x16x32_bf16 v[68:71], v[164:167], v[204:207], v[68:71]
	v_mfma_f32_16x16x32_bf16 v[64:67], v[172:175], v[204:207], v[64:67]
	s_barrier
	s_add_u32 s64, s62, 0x8000
	s_addc_u32 s65, s63, 0
	s_add_i32 m0, s30, 0x18000
	ds_read_b128 v[176:179], v163 offset:49152
	ds_read_b128 v[180:183], v163 offset:50176
	ds_read_b128 v[184:187], v163 offset:51200
	ds_read_b128 v[188:191], v163 offset:52224
	ds_read_b128 v[192:195], v163 offset:53248
	ds_read_b128 v[196:199], v163 offset:54272
	ds_read_b128 v[200:203], v163 offset:55296
	ds_read_b128 v[204:207], v163 offset:56320
	global_load_lds_dwordx4 v148, s[64:65]
	s_add_i32 m0, s30, 0x1a000
	s_add_u32 s62, s62, 0xc000
	s_addc_u32 s63, s63, 0
	global_load_lds_dwordx4 v144, s[64:65]
	s_add_i32 m0, s30, 0x1c000
	s_nop 0
	global_load_lds_dwordx4 v148, s[62:63]
	s_add_i32 m0, s30, 0x1e000
	s_nop 0
	global_load_lds_dwordx4 v144, s[62:63]
	s_mov_b32 m0, s54
	s_nop 0
	global_load_lds_dwordx4 v150, s[20:21]
	s_mov_b32 m0, s55
	s_nop 0
	global_load_lds_dwordx4 v146, s[20:21]
	s_waitcnt vmcnt(8) lgkmcnt(0)
	s_barrier
	v_mfma_f32_16x16x32_bf16 v[60:63], v[128:131], v[176:179], v[60:63]
	v_mfma_f32_16x16x32_bf16 v[56:59], v[136:139], v[176:179], v[56:59]
	v_mfma_f32_16x16x32_bf16 v[44:47], v[128:131], v[184:187], v[44:47]
	v_mfma_f32_16x16x32_bf16 v[40:43], v[136:139], v[184:187], v[40:43]
	v_mfma_f32_16x16x32_bf16 v[28:31], v[128:131], v[192:195], v[28:31]
	v_mfma_f32_16x16x32_bf16 v[24:27], v[136:139], v[192:195], v[24:27]
	v_mfma_f32_16x16x32_bf16 v[12:15], v[128:131], v[200:203], v[12:15]
	v_mfma_f32_16x16x32_bf16 v[8:11], v[136:139], v[200:203], v[8:11]
	v_mfma_f32_16x16x32_bf16 v[60:63], v[132:135], v[180:183], v[60:63]
	v_mfma_f32_16x16x32_bf16 v[56:59], v[140:143], v[180:183], v[56:59]
	v_mfma_f32_16x16x32_bf16 v[44:47], v[132:135], v[188:191], v[44:47]
	v_mfma_f32_16x16x32_bf16 v[40:43], v[140:143], v[188:191], v[40:43]
	v_mfma_f32_16x16x32_bf16 v[28:31], v[132:135], v[196:199], v[28:31]
	v_mfma_f32_16x16x32_bf16 v[24:27], v[140:143], v[196:199], v[24:27]
	v_mfma_f32_16x16x32_bf16 v[12:15], v[132:135], v[204:207], v[12:15]
	v_mfma_f32_16x16x32_bf16 v[8:11], v[140:143], v[204:207], v[8:11]
	v_mfma_f32_16x16x32_bf16 v[52:55], v[156:159], v[176:179], v[52:55]
	v_mfma_f32_16x16x32_bf16 v[48:51], v[168:171], v[176:179], v[48:51]
	v_mfma_f32_16x16x32_bf16 v[36:39], v[156:159], v[184:187], v[36:39]
	v_mfma_f32_16x16x32_bf16 v[32:35], v[168:171], v[184:187], v[32:35]
	v_mfma_f32_16x16x32_bf16 v[20:23], v[156:159], v[192:195], v[20:23]
	v_mfma_f32_16x16x32_bf16 v[16:19], v[168:171], v[192:195], v[16:19]
	v_mfma_f32_16x16x32_bf16 v[4:7], v[156:159], v[200:203], v[4:7]
	v_mfma_f32_16x16x32_bf16 v[0:3], v[168:171], v[200:203], v[0:3]
	v_mfma_f32_16x16x32_bf16 v[52:55], v[164:167], v[180:183], v[52:55]
	v_mfma_f32_16x16x32_bf16 v[48:51], v[172:175], v[180:183], v[48:51]
	v_mfma_f32_16x16x32_bf16 v[36:39], v[164:167], v[188:191], v[36:39]
	v_mfma_f32_16x16x32_bf16 v[32:35], v[172:175], v[188:191], v[32:35]
	v_mfma_f32_16x16x32_bf16 v[20:23], v[164:167], v[196:199], v[20:23]
	v_mfma_f32_16x16x32_bf16 v[16:19], v[172:175], v[196:199], v[16:19]
	v_mfma_f32_16x16x32_bf16 v[4:7], v[164:167], v[204:207], v[4:7]
	v_mfma_f32_16x16x32_bf16 v[0:3], v[172:175], v[204:207], v[0:3]
	s_barrier
	s_add_i32 s68, s68, 2
	s_cmp_gt_u32 s68, 13
	s_cbranch_scc0 .LBB0_1356
	s_and_b64 vcc, exec, s[6:7]
	s_cbranch_vccz .LBB0_1359
	s_barrier
